# attention PV block hand-scheduled (V-fragment reads bursted per slice into fresh registers, two row-sum accumulators); first slice's exp/cvt and V reads moved into the shadow of the last QK MFMAs
# speedup vs baseline: 1.0048x; 1.0048x over previous
; #define LAS __attribute__((address_space(3)))
; DI unsigned pk2(float lo, float hi) { f32x2 v = {lo, hi}; bf16x2_t b = __builtin_convertvector(v, bf16x2_t); return __builtin_bit_cast(unsigned, b); }
; #define MFMA32(a, b, c) __builtin_amdgcn_mfma_f32_32x32x16_bf16((a), (b), (c), 0, 0, 0)
; template <int NK32>
; DI void attn_tile(const LAS unsigned char* Kb, const LAS unsigned char* Vb, int map, int lane, const bf16x8 (&Q)[4], f32x16 (&O)[4], float& m, float& l) {
;     ...
;     float ps = 0.f;
; #pragma unroll
;     for (int kt = 0; kt < NK32; ++kt)
; #pragma unroll
;         for (int i = 0; i < 16; ++i) { const float p = __builtin_amdgcn_exp2f(S[kt][i] - m); S[kt][i] = p; ps += p; }
;     l += ps;
; #pragma unroll
;     for (int sl = 0; sl < 2 * NK32; ++sl) {
;         const int kt = sl >> 1, r0 = 8 * (sl & 1);
;         v4u pu; pu.x = pk2(S[kt][r0 + 0], S[kt][r0 + 1]); pu.y = pk2(S[kt][r0 + 2], S[kt][r0 + 3]); pu.z = pk2(S[kt][r0 + 4], S[kt][r0 + 5]); pu.w = pk2(S[kt][r0 + 6], S[kt][r0 + 7]);
;         const bf16x8 pf = __builtin_bit_cast(bf16x8, pu);
; #pragma unroll
;         for (int dt = 0; dt < 4; ++dt) {
;             const bf16x8 vf = *(const LAS bf16x8*)(Vb + (dt * 32 + r32) * 144 + sl * 32 + hf * 16);
;             O[dt] = MFMA32(vf, pf, O[dt]);
;         }
;     }
; DI void attn_prompt_item(const __attribute__((address_space(4))) Args& a, LAS unsigned char* lds, int ws_, int b, int h, int qt, float lam, bool dry = false) {
;     ...
;         if (more) {
; #pragma unroll
;             for (int i = 0; i < 2; ++i) { kx[i] = *(const v4u*)(ksrc[i] + (size_t)(kt + 1) * 64 * 1024); vx[i] = *(const v4u*)(vsrc[i] + (kt + 1) * 64); }
;         }
;         const LAS unsigned char* buf = lds + (kt & 1) * KV_BYTES;
;         if (kt < my_nt) attn_tile<2>(buf, buf + KT_BYTES, map, lane, Q, O, m, l);
;         if (more) {
;             LAS unsigned char* nb = lds + ((kt + 1) & 1) * KV_BYTES;
; #pragma unroll
;             for (int i = 0; i < 2; ++i) { *(LAS v4u*)(nb + kdst[i]) = kx[i]; *(LAS v4u*)(nb + vdst[i]) = vx[i]; }
;         }
;         __syncthreads();
.LBB0_1431:
	s_sub_i32 s11, 0x8c00, s10
	v_add_u32_e32 v210, s11, v132
	v_add_u32_e32 v211, s11, v134
	v_add_u32_e32 v212, s11, v136
	v_add_u32_e32 v213, s11, v138
	ds_read_b128 v[232:235], v253 offset:17440
	ds_read_b128 v[236:239], v254 offset:17440
	ds_read_b128 v[240:243], v253 offset:26656
	ds_read_b128 v[244:247], v252 offset:17440
	s_waitcnt lgkmcnt(4)
	v_mfma_f32_32x32x16_bf16 v[48:63], v[214:217], v[164:167], v[48:63]
	v_exp_f32_e32 v156, v88
	v_exp_f32_e32 v157, v89
	v_exp_f32_e32 v158, v90
	v_exp_f32_e32 v159, v91
	v_add_f32_e32 v168, v156, v168
	v_mfma_f32_32x32x16_bf16 v[32:47], v[218:221], v[164:167], v[32:47]
	v_exp_f32_e32 v160, v92
	v_exp_f32_e32 v161, v93
	v_add_f32_e32 v169, v157, v169
	v_add_f32_e32 v168, v158, v168
	v_cvt_pk_bf16_f32 v176, v156, v157
	v_mfma_f32_32x32x16_bf16 v[16:31], v[222:225], v[164:167], v[16:31]
	v_exp_f32_e32 v162, v94
	v_exp_f32_e32 v163, v95
	v_add_f32_e32 v169, v159, v169
	v_add_f32_e32 v168, v160, v168
	v_cvt_pk_bf16_f32 v177, v158, v159
	v_mfma_f32_32x32x16_bf16 v[0:15], v[226:229], v[164:167], v[0:15]
	s_waitcnt vmcnt(3)
	ds_write_b128 v210, v[118:121]
	ds_read_b128 v[214:217], v253 offset:17472
	ds_read_b128 v[218:221], v254 offset:17472
	ds_read_b128 v[222:225], v253 offset:26688
	ds_read_b128 v[226:229], v252 offset:17472
	v_cvt_pk_bf16_f32 v178, v160, v161
	v_cvt_pk_bf16_f32 v179, v162, v163
	v_add_f32_e32 v169, v161, v169
	v_add_f32_e32 v168, v162, v168
	v_add_f32_e32 v169, v163, v169
	s_waitcnt lgkmcnt(5)
	v_mfma_f32_32x32x16_bf16 v[48:63], v[232:235], v[176:179], v[48:63]
	v_exp_f32_e32 v156, v64
	v_exp_f32_e32 v157, v65
	v_exp_f32_e32 v158, v66
	v_exp_f32_e32 v159, v67
	v_add_f32_e32 v168, v156, v168
	v_mfma_f32_32x32x16_bf16 v[32:47], v[236:239], v[176:179], v[32:47]
	v_exp_f32_e32 v160, v68
	v_exp_f32_e32 v161, v69
	v_add_f32_e32 v169, v157, v169
	v_add_f32_e32 v168, v158, v168
	v_cvt_pk_bf16_f32 v164, v156, v157
	v_mfma_f32_32x32x16_bf16 v[16:31], v[240:243], v[176:179], v[16:31]
	s_waitcnt vmcnt(2)
	ds_write_b128 v211, v[114:117] offset:17408
	v_exp_f32_e32 v162, v70
	v_exp_f32_e32 v163, v71
	v_add_f32_e32 v169, v159, v169
	v_add_f32_e32 v168, v160, v168
	v_cvt_pk_bf16_f32 v165, v158, v159
	v_mfma_f32_32x32x16_bf16 v[0:15], v[244:247], v[176:179], v[0:15]
	ds_read_b128 v[232:235], v253 offset:17504
	ds_read_b128 v[236:239], v254 offset:17504
	ds_read_b128 v[240:243], v253 offset:26720
	ds_read_b128 v[244:247], v252 offset:17504
	v_cvt_pk_bf16_f32 v166, v160, v161
	v_cvt_pk_bf16_f32 v167, v162, v163
	v_add_f32_e32 v169, v161, v169
	v_add_f32_e32 v168, v162, v168
	v_add_f32_e32 v169, v163, v169
	s_waitcnt lgkmcnt(5)
	v_mfma_f32_32x32x16_bf16 v[48:63], v[214:217], v[164:167], v[48:63]
	v_exp_f32_e32 v156, v72
	v_exp_f32_e32 v157, v73
	v_exp_f32_e32 v158, v74
	v_exp_f32_e32 v159, v75
	v_add_f32_e32 v168, v156, v168
	v_mfma_f32_32x32x16_bf16 v[32:47], v[218:221], v[164:167], v[32:47]
	s_waitcnt vmcnt(1)
	ds_write_b128 v212, v[126:129]
	v_exp_f32_e32 v160, v76
	v_exp_f32_e32 v161, v77
	v_add_f32_e32 v169, v157, v169
	v_add_f32_e32 v168, v158, v168
	v_cvt_pk_bf16_f32 v176, v156, v157
	v_mfma_f32_32x32x16_bf16 v[16:31], v[222:225], v[164:167], v[16:31]
	v_exp_f32_e32 v162, v78
	v_exp_f32_e32 v163, v79
	v_add_f32_e32 v169, v159, v169
	v_add_f32_e32 v168, v160, v168
	v_cvt_pk_bf16_f32 v177, v158, v159
	v_mfma_f32_32x32x16_bf16 v[0:15], v[226:229], v[164:167], v[0:15]
	v_cvt_pk_bf16_f32 v178, v160, v161
	v_cvt_pk_bf16_f32 v179, v162, v163
	v_add_f32_e32 v169, v161, v169
	v_add_f32_e32 v168, v162, v168
	v_add_f32_e32 v169, v163, v169
	s_waitcnt lgkmcnt(1)
	v_mfma_f32_32x32x16_bf16 v[48:63], v[232:235], v[176:179], v[48:63]
	s_waitcnt vmcnt(0)
	ds_write_b128 v213, v[122:125] offset:17408
	v_mfma_f32_32x32x16_bf16 v[32:47], v[236:239], v[176:179], v[32:47]
	v_mfma_f32_32x32x16_bf16 v[16:31], v[240:243], v[176:179], v[16:31]
	v_mfma_f32_32x32x16_bf16 v[0:15], v[244:247], v[176:179], v[0:15]
	v_add_f32_e32 v168, v168, v169
	v_add_f32_e32 v133, v133, v168
	s_add_i32 s9, s9, 1
	s_bitcmp1_b32 s9, 0
	s_cselect_b32 s10, 0x8c00, 0
	v_lshl_add_u64 v[140:141], v[140:141], 0, s[28:29]
	v_lshl_add_u64 v[142:143], v[142:143], 0, s[28:29]
	v_lshl_add_u64 v[144:145], v[144:145], 0, s[30:31]
	s_cmp_eq_u32 s8, s9
	v_lshl_add_u64 v[146:147], v[146:147], 0, s[30:31]
	s_cbranch_scc1 .Lnold_a
	v_lshl_add_u64 v[228:229], s[36:37], 0, v[146:147]
	v_lshl_add_u64 v[230:231], s[36:37], 0, v[142:143]
	global_load_dwordx4 v[118:121], v[228:229], off
	global_load_dwordx4 v[114:117], v[230:231], off
	v_lshl_add_u64 v[228:229], s[36:37], 0, v[144:145]
	v_lshl_add_u64 v[230:231], s[36:37], 0, v[140:141]
	global_load_dwordx4 v[126:129], v[228:229], off
	global_load_dwordx4 v[122:125], v[230:231], off

; #define LAS __attribute__((address_space(3)))
; DI unsigned pk2(float lo, float hi) { f32x2 v = {lo, hi}; bf16x2_t b = __builtin_convertvector(v, bf16x2_t); return __builtin_bit_cast(unsigned, b); }
; DI float half_max(float v) { auto rr = __builtin_amdgcn_permlane32_swap(__float_as_uint(v), __float_as_uint(v), false, false); return fmaxf(__uint_as_float(rr[0]), __uint_as_float(rr[1])); }
; #define MFMA32(a, b, c) __builtin_amdgcn_mfma_f32_32x32x16_bf16((a), (b), (c), 0, 0, 0)
; template <int NK32>
; DI void attn_tile(const LAS unsigned char* Kb, const LAS unsigned char* Vb, int map, int lane, const bf16x8 (&Q)[4], f32x16 (&O)[4], float& m, float& l) {
;     ...
;     __builtin_amdgcn_s_setprio(1);
; #pragma unroll
;     for (int kt = 0; kt < NK32; ++kt) {
; #pragma unroll
;         for (int i = 0; i < 16; ++i) S[kt][i] = 0.f;
; #pragma unroll
;         for (int ds = 0; ds < 4; ++ds) {
;             const bf16x8 kf = *(const LAS bf16x8*)(Kb + (kt * 32 + r32) * 272 + map * 128 + ds * 32 + hf * 16);
;             S[kt] = MFMA32(kf, Q[ds], S[kt]);
;         }
;     }
;     __builtin_amdgcn_s_setprio(0);
;     float mx = fmaxf(S[0][0], S[0][1]);
; #pragma unroll
;     for (int kt = 0; kt < NK32; ++kt)
; #pragma unroll
;         for (int i = (kt == 0 ? 2 : 0); i < 16; i += 2) mx = fmaxf(fmaxf(mx, S[kt][i]), S[kt][i + 1]);
;     mx = half_max(mx);
;     if (__any(mx > m + 8.f)) {
;         const float mn = fmaxf(m, mx);
;         const float alpha = __builtin_amdgcn_exp2f(m - mn);
;         m = mn; l *= alpha;
; #pragma unroll
;         for (int dt = 0; dt < 4; ++dt)
; #pragma unroll
;             for (int i = 0; i < 16; ++i) O[dt][i] *= alpha;
;     }
;     float ps = 0.f;
; #pragma unroll
;     for (int kt = 0; kt < NK32; ++kt)
; #pragma unroll
;         for (int i = 0; i < 16; ++i) { const float p = __builtin_amdgcn_exp2f(S[kt][i] - m); S[kt][i] = p; ps += p; }
;     l += ps;
; #pragma unroll
;     for (int sl = 0; sl < 2 * NK32; ++sl) {
;         const int kt = sl >> 1, r0 = 8 * (sl & 1);
;         v4u pu; pu.x = pk2(S[kt][r0 + 0], S[kt][r0 + 1]); pu.y = pk2(S[kt][r0 + 2], S[kt][r0 + 3]); pu.z = pk2(S[kt][r0 + 4], S[kt][r0 + 5]); pu.w = pk2(S[kt][r0 + 6], S[kt][r0 + 7]);
.LBB0_1433:
	s_cmp_ge_u32 s9, s7
	s_cbranch_scc1 .LBB0_1432
	s_bitcmp1_b32 s9, 0
	s_cselect_b32 s10, 0x8c00, 0
	s_add_i32 s10, s10, 0
	s_setprio 1
	s_add_i32 s11, s10, s89
	v_add_u32_e32 v72, s11, v130
	v_add_u32_e32 v73, v72, v153
	v_add_u32_e32 v155, v72, v154
	ds_read_b128 v[64:67], v73
	ds_read_b128 v[68:71], v73 offset:32
	ds_read_b128 v[232:235], v73 offset:64
	ds_read_b128 v[236:239], v73 offset:96
	ds_read_b128 v[240:243], v155
	ds_read_b128 v[244:247], v155 offset:32
	ds_read_b128 v[248:251], v155 offset:64
	ds_read_b128 v[184:187], v155 offset:96
	s_waitcnt vmcnt(7) lgkmcnt(7)
	v_mfma_f32_32x32x16_bf16 v[80:95], v[64:67], v[110:113], v[192:207]
	s_waitcnt vmcnt(6) lgkmcnt(6)
	v_mfma_f32_32x32x16_bf16 v[80:95], v[68:71], v[106:109], v[80:95]
	s_waitcnt vmcnt(5) lgkmcnt(5)
	v_mfma_f32_32x32x16_bf16 v[80:95], v[232:235], v[102:105], v[80:95]
	s_waitcnt vmcnt(4) lgkmcnt(4)
	v_mfma_f32_32x32x16_bf16 v[80:95], v[236:239], v[98:101], v[80:95]
	s_waitcnt lgkmcnt(3)
	v_mfma_f32_32x32x16_bf16 v[64:79], v[240:243], v[110:113], v[192:207]
	s_waitcnt lgkmcnt(2)
	v_mfma_f32_32x32x16_bf16 v[64:79], v[244:247], v[106:109], v[64:79]
	v_add_u32_e32 v252, s10, v130
	v_add_u32_e32 v253, v252, v139
	v_add_u32_e32 v254, v252, v137
	v_add_u32_e32 v252, v252, v135
	ds_read_b128 v[214:217], v253 offset:17408
	ds_read_b128 v[218:221], v254 offset:17408
	ds_read_b128 v[222:225], v253 offset:26624
	ds_read_b128 v[226:229], v252 offset:17408
	v_mov_b32_e32 v168, 0
	v_mov_b32_e32 v169, 0
	v_exp_f32_e32 v156, v80
	v_exp_f32_e32 v157, v81
	v_exp_f32_e32 v158, v82
	v_exp_f32_e32 v159, v83
	v_add_f32_e32 v168, v156, v168
	v_exp_f32_e32 v160, v84
	v_exp_f32_e32 v161, v85
	v_add_f32_e32 v169, v157, v169
	v_add_f32_e32 v168, v158, v168
	v_cvt_pk_bf16_f32 v164, v156, v157
	s_waitcnt lgkmcnt(5)
	v_mfma_f32_32x32x16_bf16 v[64:79], v[248:251], v[102:105], v[64:79]
	v_exp_f32_e32 v162, v86
	v_exp_f32_e32 v163, v87
	v_add_f32_e32 v169, v159, v169
	v_add_f32_e32 v168, v160, v168
	v_cvt_pk_bf16_f32 v165, v158, v159
	v_cvt_pk_bf16_f32 v166, v160, v161
	v_cvt_pk_bf16_f32 v167, v162, v163
	v_add_f32_e32 v169, v161, v169
	v_add_f32_e32 v168, v162, v168
	v_add_f32_e32 v169, v163, v169
	s_waitcnt lgkmcnt(4)
	v_mfma_f32_32x32x16_bf16 v[64:79], v[184:187], v[98:101], v[64:79]
	s_setprio 0
	s_nop 0
	v_max_f32_e32 v155, v81, v81
	v_max_f32_e32 v156, v80, v80
	v_max_f32_e32 v155, v156, v155
	v_max3_f32 v155, v155, v82, v83
	v_max3_f32 v155, v155, v84, v85
	v_max3_f32 v155, v155, v86, v87
	v_max3_f32 v155, v155, v88, v89
	v_max3_f32 v155, v155, v90, v91
	v_max3_f32 v155, v155, v92, v93
	v_max3_f32 v155, v155, v94, v95
	v_max3_f32 v155, v155, v64, v65
	v_max3_f32 v155, v155, v66, v67
	v_max3_f32 v155, v155, v68, v69
	v_max3_f32 v155, v155, v70, v71
	v_max3_f32 v155, v155, v72, v73
	v_max3_f32 v155, v155, v74, v75
	v_max3_f32 v155, v155, v76, v77
	v_max3_f32 v155, v155, v78, v79
	v_mov_b32_e32 v156, v155
	s_nop 1
	v_permlane32_swap_b32_e32 v155, v156
	v_max_f32_e32 v156, v156, v156
	v_max_f32_e32 v155, v155, v155
	v_max_f32_e32 v155, v155, v156
	v_cmp_gt_f32_e32 vcc, v155, v152
	s_cbranch_vccz .LBB0_1431
; DI unsigned pk2(float lo, float hi) { f32x2 v = {lo, hi}; bf16x2_t b = __builtin_convertvector(v, bf16x2_t); return __builtin_bit_cast(unsigned, b); }
; template <int NK32>
; DI void attn_tile(const LAS unsigned char* Kb, const LAS unsigned char* Vb, int map, int lane, const bf16x8 (&Q)[4], f32x16 (&O)[4], float& m, float& l) {
;     ...
;     if (__any(mx > m + 8.f)) {
;         const float mn = fmaxf(m, mx);
;         const float alpha = __builtin_amdgcn_exp2f(m - mn);
;         m = mn; l *= alpha;
; #pragma unroll
;         for (int dt = 0; dt < 4; ++dt)
; #pragma unroll
;             for (int i = 0; i < 16; ++i) O[dt][i] *= alpha;
;     }
;     float ps = 0.f;
; #pragma unroll
;     for (int kt = 0; kt < NK32; ++kt)
; #pragma unroll
;         for (int i = 0; i < 16; ++i) { const float p = __builtin_amdgcn_exp2f(S[kt][i] - m); S[kt][i] = p; ps += p; }
;     l += ps;
; #pragma unroll
;     for (int sl = 0; sl < 2 * NK32; ++sl) {
;         const int kt = sl >> 1, r0 = 8 * (sl & 1);
;         v4u pu; pu.x = pk2(S[kt][r0 + 0], S[kt][r0 + 1]); pu.y = pk2(S[kt][r0 + 2], S[kt][r0 + 3]); pu.z = pk2(S[kt][r0 + 4], S[kt][r0 + 5]); pu.w = pk2(S[kt][r0 + 6], S[kt][r0 + 7]);
	v_max_f32_e32 v155, v155, v209
	v_max_f32_e32 v156, 0, v155
	v_mul_f32_e32 v156, -1.0, v156
	v_exp_f32_e32 v156, v156
	v_sub_f32_e32 v192, v192, v155
	v_mov_b32_e32 v152, 0x41000000
	v_mov_b32_e32 v209, 0
	v_sub_f32_e32 v80, v80, v155
	v_sub_f32_e32 v81, v81, v155
	v_sub_f32_e32 v82, v82, v155
	v_sub_f32_e32 v83, v83, v155
	v_sub_f32_e32 v84, v84, v155
	v_sub_f32_e32 v85, v85, v155
	v_sub_f32_e32 v86, v86, v155
	v_sub_f32_e32 v87, v87, v155
	v_sub_f32_e32 v88, v88, v155
	v_sub_f32_e32 v89, v89, v155
	v_sub_f32_e32 v90, v90, v155
	v_sub_f32_e32 v91, v91, v155
	v_sub_f32_e32 v92, v92, v155
	v_sub_f32_e32 v93, v93, v155
	v_sub_f32_e32 v94, v94, v155
	v_sub_f32_e32 v95, v95, v155
	v_sub_f32_e32 v64, v64, v155
	v_sub_f32_e32 v65, v65, v155
	v_sub_f32_e32 v66, v66, v155
	v_sub_f32_e32 v67, v67, v155
	v_sub_f32_e32 v68, v68, v155
	v_sub_f32_e32 v69, v69, v155
	v_sub_f32_e32 v70, v70, v155
	v_sub_f32_e32 v71, v71, v155
	v_sub_f32_e32 v72, v72, v155
	v_sub_f32_e32 v73, v73, v155
	v_sub_f32_e32 v74, v74, v155
	v_sub_f32_e32 v75, v75, v155
	v_sub_f32_e32 v76, v76, v155
	v_sub_f32_e32 v77, v77, v155
	v_sub_f32_e32 v78, v78, v155
	v_sub_f32_e32 v79, v79, v155
	v_mov_b32_e32 v193, v192
	v_mov_b32_e32 v194, v192
	v_mov_b32_e32 v195, v192
	v_mov_b32_e32 v196, v192
	v_mov_b32_e32 v197, v192
	v_mov_b32_e32 v198, v192
	v_mov_b32_e32 v199, v192
	v_mov_b32_e32 v200, v192
	v_mov_b32_e32 v201, v192
	v_mov_b32_e32 v202, v192
	v_mov_b32_e32 v203, v192
	v_mov_b32_e32 v204, v192
	v_mov_b32_e32 v205, v192
	v_mov_b32_e32 v206, v192
	v_mov_b32_e32 v207, v192
	v_mul_f32_e32 v133, v133, v156
	v_pk_mul_f32 v[62:63], v[62:63], v[156:157] op_sel_hi:[1,0]
	v_pk_mul_f32 v[60:61], v[60:61], v[156:157] op_sel_hi:[1,0]
	v_pk_mul_f32 v[58:59], v[58:59], v[156:157] op_sel_hi:[1,0]
	v_pk_mul_f32 v[56:57], v[56:57], v[156:157] op_sel_hi:[1,0]
	v_pk_mul_f32 v[54:55], v[54:55], v[156:157] op_sel_hi:[1,0]
	v_pk_mul_f32 v[52:53], v[52:53], v[156:157] op_sel_hi:[1,0]
	v_pk_mul_f32 v[50:51], v[50:51], v[156:157] op_sel_hi:[1,0]
	v_pk_mul_f32 v[48:49], v[48:49], v[156:157] op_sel_hi:[1,0]
	v_pk_mul_f32 v[46:47], v[46:47], v[156:157] op_sel_hi:[1,0]
	v_pk_mul_f32 v[44:45], v[44:45], v[156:157] op_sel_hi:[1,0]
	v_pk_mul_f32 v[42:43], v[42:43], v[156:157] op_sel_hi:[1,0]
	v_pk_mul_f32 v[40:41], v[40:41], v[156:157] op_sel_hi:[1,0]
	v_pk_mul_f32 v[38:39], v[38:39], v[156:157] op_sel_hi:[1,0]
	v_pk_mul_f32 v[36:37], v[36:37], v[156:157] op_sel_hi:[1,0]
	v_pk_mul_f32 v[34:35], v[34:35], v[156:157] op_sel_hi:[1,0]
	v_pk_mul_f32 v[32:33], v[32:33], v[156:157] op_sel_hi:[1,0]
	v_pk_mul_f32 v[30:31], v[30:31], v[156:157] op_sel_hi:[1,0]
	v_pk_mul_f32 v[28:29], v[28:29], v[156:157] op_sel_hi:[1,0]
	v_pk_mul_f32 v[26:27], v[26:27], v[156:157] op_sel_hi:[1,0]
	v_pk_mul_f32 v[24:25], v[24:25], v[156:157] op_sel_hi:[1,0]
	v_pk_mul_f32 v[22:23], v[22:23], v[156:157] op_sel_hi:[1,0]
	v_pk_mul_f32 v[20:21], v[20:21], v[156:157] op_sel_hi:[1,0]
	v_pk_mul_f32 v[18:19], v[18:19], v[156:157] op_sel_hi:[1,0]
	v_pk_mul_f32 v[16:17], v[16:17], v[156:157] op_sel_hi:[1,0]
	v_pk_mul_f32 v[14:15], v[14:15], v[156:157] op_sel_hi:[1,0]
	v_pk_mul_f32 v[12:13], v[12:13], v[156:157] op_sel_hi:[1,0]
	v_pk_mul_f32 v[10:11], v[10:11], v[156:157] op_sel_hi:[1,0]
	v_pk_mul_f32 v[8:9], v[8:9], v[156:157] op_sel_hi:[1,0]
	v_pk_mul_f32 v[6:7], v[6:7], v[156:157] op_sel_hi:[1,0]
	v_pk_mul_f32 v[4:5], v[4:5], v[156:157] op_sel_hi:[1,0]
	v_pk_mul_f32 v[2:3], v[2:3], v[156:157] op_sel_hi:[1,0]
	v_pk_mul_f32 v[0:1], v[0:1], v[156:157] op_sel_hi:[1,0]
	v_mov_b32_e32 v168, 0
	v_mov_b32_e32 v169, 0
	v_exp_f32_e32 v156, v80
	v_exp_f32_e32 v157, v81
	v_exp_f32_e32 v158, v82
	v_exp_f32_e32 v159, v83
	v_add_f32_e32 v168, v156, v168
	v_exp_f32_e32 v160, v84
	v_exp_f32_e32 v161, v85
	v_add_f32_e32 v169, v157, v169
	v_add_f32_e32 v168, v158, v168
	v_cvt_pk_bf16_f32 v164, v156, v157
	v_exp_f32_e32 v162, v86
	v_exp_f32_e32 v163, v87
	v_add_f32_e32 v169, v159, v169
	v_add_f32_e32 v168, v160, v168
	v_cvt_pk_bf16_f32 v165, v158, v159
	v_cvt_pk_bf16_f32 v166, v160, v161
	v_cvt_pk_bf16_f32 v167, v162, v163
	v_add_f32_e32 v169, v161, v169
	v_add_f32_e32 v168, v162, v168
	v_add_f32_e32 v169, v163, v169
	s_branch .LBB0_1431

; DI void scan_item(const __attribute__((address_space(4))) Args& a, LAS unsigned char* lds, int ws_, bool is_prompt, int seq, int h, int half, bool dry = false) {
;     ...
;     auto consume = [&](int bsel) {
;         const LAS unsigned char* B = lds + bsel * SC_BUF;
;         const LAS float* opb = (const LAS float*)B + c0;
;         const LAS float* vvb = (const LAS float*)(B + SC_OPS) + i0;
;         const LAS float* scb = (const LAS float*)(B + SC_OPS + SC_VV);
;         LAS float* ybb = cg8 == 0 ? (LAS float*)(B + SC_OPS + SC_VV + SC_SC) + (i0 & 31) : (LAS float*)(lds + 2 * SC_BUF) + (tid & 255);
;         f32x4 n[10]; float nv; f32x2 nbk;
;     ...
;         SC_LOAD(0)
; #pragma unroll 4
;         for (int t = 0; t < SC_CH; ++t) {
;             f32x4 c[10];
; #pragma unroll
;             for (int q = 0; q < 10; ++q) c[q] = n[q];
;             const float v0 = nv; const f32x2 bk = nbk;
;             SC_LOAD(t + 1)
;             __builtin_amdgcn_sched_barrier(0);
;             f32x2 aA = sp[0] * c[0].xy, aY = sp[0] * c[2].xy;
;             aA = sp[1] * c[0].zw + aA; aY = sp[1] * c[2].zw + aY;
;             aA = sp[2] * c[1].xy + aA; aY = sp[2] * c[3].xy + aY;
;             aA = sp[3] * c[1].zw + aA; aY = sp[3] * c[3].zw + aY;
;             float da = aA.x + aA.y, dy = aY.x + aY.y;
;             asm("s_nop 1\n\t"
;                 "v_add_f32_dpp %0, %0, %0 quad_perm:[1,0,3,2] row_mask:0xf bank_mask:0xf bound_ctrl:1\n\t"
;                 "v_add_f32_dpp %1, %1, %1 quad_perm:[1,0,3,2] row_mask:0xf bank_mask:0xf bound_ctrl:1\n\t"
;                 "s_nop 0\n\t"
;                 "v_add_f32_dpp %0, %0, %0 quad_perm:[2,3,0,1] row_mask:0xf bank_mask:0xf bound_ctrl:1\n\t"
;                 "v_add_f32_dpp %1, %1, %1 quad_perm:[2,3,0,1] row_mask:0xf bank_mask:0xf bound_ctrl:1\n\t"
;                 "s_nop 0\n\t"
;                 "v_add_f32_dpp %0, %0, %0 row_half_mirror row_mask:0xf bank_mask:0xf bound_ctrl:1\n\t"
;                 "v_add_f32_dpp %1, %1, %1 row_half_mirror row_mask:0xf bank_mask:0xf bound_ctrl:1"
;                 : "+v"(da), "+v"(dy));
;             {
;                 f32x2 t0;
;                 t0 = c[8].xy * v0; t0 = c[6].xy * da + t0; sp[0] = sp[0] * c[4].xy + t0;
;                 t0 = c[8].zw * v0; t0 = c[6].zw * da + t0; sp[1] = sp[1] * c[4].zw + t0;
;                 t0 = c[9].xy * v0; t0 = c[7].xy * da + t0; sp[2] = sp[2] * c[5].xy + t0;
.LBB0_1535:
	s_and_b64 vcc, exec, s[74:75]
	s_cbranch_vccz .LBB0_1523
	s_bitcmp1_b32 s24, 0
	s_cselect_b32 s34, 0x6900, 0
	s_add_i32 s35, s34, 0
	s_waitcnt vmcnt(0)
	v_lshl_add_u32 v120, v110, 2, s35
	v_lshl_add_u32 v96, v111, 2, s35
	v_lshl_add_u32 v136, v115, 2, s35
	v_mov_b32_e32 v121, s35
	v_add_u32_e32 v136, 0x6100, v136
	v_cndmask_b32_e64 v95, v116, v136, s[8:9]
	ds_read_b128 v[40:43], v120
	ds_read_b128 v[44:47], v120 offset:16
	ds_read_b128 v[48:51], v120 offset:256
	ds_read_b128 v[52:55], v120 offset:272
	ds_read_b128 v[56:59], v120 offset:512
	ds_read_b128 v[60:63], v120 offset:528
	ds_read_b128 v[64:67], v120 offset:768
	ds_read_b128 v[68:71], v120 offset:784
	ds_read_b128 v[72:75], v120 offset:1024
	ds_read_b128 v[76:79], v120 offset:1040
	ds_read_b32 v94, v96 offset:20480
	ds_read_b64 v[108:109], v121 offset:24576
	ds_read_b128 v[190:193], v120 offset:1280
	ds_read_b128 v[194:197], v120 offset:1296
	ds_read_b128 v[198:201], v120 offset:1536
	ds_read_b128 v[202:205], v120 offset:1552
	ds_read_b128 v[206:209], v120 offset:1792
	ds_read_b128 v[210:213], v120 offset:1808
	ds_read_b128 v[214:217], v120 offset:2048
	ds_read_b128 v[218:221], v120 offset:2064
	ds_read_b128 v[222:225], v120 offset:2304
	ds_read_b128 v[226:229], v120 offset:2320
	ds_read_b32 v230, v96 offset:20736
	ds_read_b64 v[232:233], v121 offset:24592
	s_waitcnt lgkmcnt(12)
	v_pk_mul_f32 v[122:123], v[38:39], v[42:43]
	v_pk_mul_f32 v[124:125], v[38:39], v[50:51]
	v_pk_fma_f32 v[122:123], v[36:37], v[40:41], v[122:123]
	v_pk_fma_f32 v[124:125], v[36:37], v[48:49], v[124:125]
	v_pk_fma_f32 v[122:123], v[32:33], v[44:45], v[122:123]
	v_pk_fma_f32 v[124:125], v[32:33], v[52:53], v[124:125]
	v_pk_fma_f32 v[122:123], v[34:35], v[46:47], v[122:123]
	v_pk_fma_f32 v[124:125], v[34:35], v[54:55], v[124:125]
	v_pk_mul_f32 v[126:127], v[72:73], v[94:95] op_sel_hi:[1,0]
	v_add_f32_e32 v166, v122, v123
	v_add_f32_e32 v168, v124, v125
	v_pk_mul_f32 v[128:129], v[74:75], v[94:95] op_sel_hi:[1,0]
	v_pk_mul_f32 v[130:131], v[76:77], v[94:95] op_sel_hi:[1,0]
	v_add_f32_dpp v166, v166, v166 quad_perm:[1,0,3,2] row_mask:0xf bank_mask:0xf bound_ctrl:1
	v_add_f32_dpp v168, v168, v168 quad_perm:[1,0,3,2] row_mask:0xf bank_mask:0xf bound_ctrl:1
	v_pk_mul_f32 v[132:133], v[78:79], v[94:95] op_sel_hi:[1,0]
	v_pk_fma_f32 v[126:127], v[36:37], v[56:57], v[126:127]
	v_add_f32_dpp v166, v166, v166 quad_perm:[2,3,0,1] row_mask:0xf bank_mask:0xf bound_ctrl:1
	v_add_f32_dpp v168, v168, v168 quad_perm:[2,3,0,1] row_mask:0xf bank_mask:0xf bound_ctrl:1
	v_pk_fma_f32 v[128:129], v[38:39], v[58:59], v[128:129]
	v_pk_fma_f32 v[130:131], v[32:33], v[60:61], v[130:131]
	v_add_f32_dpp v166, v166, v166 row_half_mirror row_mask:0xf bank_mask:0xf bound_ctrl:1
	v_add_f32_dpp v168, v168, v168 row_half_mirror row_mask:0xf bank_mask:0xf bound_ctrl:1
	v_pk_fma_f32 v[132:133], v[34:35], v[62:63], v[132:133]
	v_mov_b32_e32 v167, v94
	v_pk_mul_f32 v[134:135], v[166:167], v[108:109]
	v_pk_fma_f32 v[36:37], v[64:65], v[166:167], v[126:127] op_sel_hi:[1,0,1]
	v_pk_fma_f32 v[38:39], v[66:67], v[166:167], v[128:129] op_sel_hi:[1,0,1]
	v_pk_fma_f32 v[32:33], v[68:69], v[166:167], v[130:131] op_sel_hi:[1,0,1]
	v_pk_fma_f32 v[34:35], v[70:71], v[166:167], v[132:133] op_sel_hi:[1,0,1]
	v_add_f32_e32 v136, v168, v134
	v_add_f32_e32 v136, v135, v136
	ds_write_b32 v95, v136
	ds_read_b128 v[40:43], v120 offset:2560
	ds_read_b128 v[44:47], v120 offset:2576
	ds_read_b128 v[48:51], v120 offset:2816
	ds_read_b128 v[52:55], v120 offset:2832
	ds_read_b128 v[56:59], v120 offset:3072
	ds_read_b128 v[60:63], v120 offset:3088
	ds_read_b128 v[64:67], v120 offset:3328
	ds_read_b128 v[68:71], v120 offset:3344
	ds_read_b128 v[72:75], v120 offset:3584
	ds_read_b128 v[76:79], v120 offset:3600
	ds_read_b32 v94, v96 offset:20992
	ds_read_b64 v[108:109], v121 offset:24608
	s_waitcnt lgkmcnt(12)
	v_pk_mul_f32 v[122:123], v[38:39], v[192:193]
	v_pk_mul_f32 v[124:125], v[38:39], v[200:201]
	v_pk_fma_f32 v[122:123], v[36:37], v[190:191], v[122:123]
	v_pk_fma_f32 v[124:125], v[36:37], v[198:199], v[124:125]
	v_pk_fma_f32 v[122:123], v[32:33], v[194:195], v[122:123]
	v_pk_fma_f32 v[124:125], v[32:33], v[202:203], v[124:125]
	v_pk_fma_f32 v[122:123], v[34:35], v[196:197], v[122:123]
	v_pk_fma_f32 v[124:125], v[34:35], v[204:205], v[124:125]
	v_pk_mul_f32 v[126:127], v[222:223], v[230:231] op_sel_hi:[1,0]
	v_add_f32_e32 v166, v122, v123
	v_add_f32_e32 v168, v124, v125
	v_pk_mul_f32 v[128:129], v[224:225], v[230:231] op_sel_hi:[1,0]
	v_pk_mul_f32 v[130:131], v[226:227], v[230:231] op_sel_hi:[1,0]
	v_add_f32_dpp v166, v166, v166 quad_perm:[1,0,3,2] row_mask:0xf bank_mask:0xf bound_ctrl:1
	v_add_f32_dpp v168, v168, v168 quad_perm:[1,0,3,2] row_mask:0xf bank_mask:0xf bound_ctrl:1
	v_pk_mul_f32 v[132:133], v[228:229], v[230:231] op_sel_hi:[1,0]
	v_pk_fma_f32 v[126:127], v[36:37], v[206:207], v[126:127]
	v_add_f32_dpp v166, v166, v166 quad_perm:[2,3,0,1] row_mask:0xf bank_mask:0xf bound_ctrl:1
	v_add_f32_dpp v168, v168, v168 quad_perm:[2,3,0,1] row_mask:0xf bank_mask:0xf bound_ctrl:1
	v_pk_fma_f32 v[128:129], v[38:39], v[208:209], v[128:129]
	v_pk_fma_f32 v[130:131], v[32:33], v[210:211], v[130:131]
	v_add_f32_dpp v166, v166, v166 row_half_mirror row_mask:0xf bank_mask:0xf bound_ctrl:1
	v_add_f32_dpp v168, v168, v168 row_half_mirror row_mask:0xf bank_mask:0xf bound_ctrl:1
	v_pk_fma_f32 v[132:133], v[34:35], v[212:213], v[132:133]
	v_mov_b32_e32 v167, v230
	v_pk_mul_f32 v[134:135], v[166:167], v[232:233]
	v_pk_fma_f32 v[36:37], v[214:215], v[166:167], v[126:127] op_sel_hi:[1,0,1]
	v_pk_fma_f32 v[38:39], v[216:217], v[166:167], v[128:129] op_sel_hi:[1,0,1]
	v_pk_fma_f32 v[32:33], v[218:219], v[166:167], v[130:131] op_sel_hi:[1,0,1]
	v_pk_fma_f32 v[34:35], v[220:221], v[166:167], v[132:133] op_sel_hi:[1,0,1]
	v_add_f32_e32 v136, v168, v134
	v_add_f32_e32 v136, v135, v136
	ds_write_b32 v95, v136 offset:128
	ds_read_b128 v[190:193], v120 offset:3840
	ds_read_b128 v[194:197], v120 offset:3856
	ds_read_b128 v[198:201], v120 offset:4096
	ds_read_b128 v[202:205], v120 offset:4112
	ds_read_b128 v[206:209], v120 offset:4352
	ds_read_b128 v[210:213], v120 offset:4368
	ds_read_b128 v[214:217], v120 offset:4608
	ds_read_b128 v[218:221], v120 offset:4624
	ds_read_b128 v[222:225], v120 offset:4864
	ds_read_b128 v[226:229], v120 offset:4880
	ds_read_b32 v230, v96 offset:21248
	ds_read_b64 v[232:233], v121 offset:24624
	s_waitcnt lgkmcnt(12)
; #define SC_LOAD(t) { _Pragma("unroll") for (int q = 0; q < 5; ++q) { n[2 * q] = *(const LAS f32x4*)(opb + (t) * 320 + q * 64); n[2 * q + 1] = *(const LAS f32x4*)(opb + (t) * 320 + q * 64 + 4); } \
;                      nv = vvb[(t) * 64]; nbk = *(const LAS f32x2*)(scb + (t) * 4); }
; DI void scan_item(const __attribute__((address_space(4))) Args& a, LAS unsigned char* lds, int ws_, bool is_prompt, int seq, int h, int half, bool dry = false) {
;     ...
;         SC_LOAD(0)
; #pragma unroll 4
;         for (int t = 0; t < SC_CH; ++t) {
;             f32x4 c[10];
; #pragma unroll
;             for (int q = 0; q < 10; ++q) c[q] = n[q];
;             const float v0 = nv; const f32x2 bk = nbk;
;             SC_LOAD(t + 1)
;             __builtin_amdgcn_sched_barrier(0);
;             f32x2 aA = sp[0] * c[0].xy, aY = sp[0] * c[2].xy;
;             aA = sp[1] * c[0].zw + aA; aY = sp[1] * c[2].zw + aY;
;             aA = sp[2] * c[1].xy + aA; aY = sp[2] * c[3].xy + aY;
;             aA = sp[3] * c[1].zw + aA; aY = sp[3] * c[3].zw + aY;
;             float da = aA.x + aA.y, dy = aY.x + aY.y;
;             asm("s_nop 1\n\t"
;                 "v_add_f32_dpp %0, %0, %0 quad_perm:[1,0,3,2] row_mask:0xf bank_mask:0xf bound_ctrl:1\n\t"
;                 "v_add_f32_dpp %1, %1, %1 quad_perm:[1,0,3,2] row_mask:0xf bank_mask:0xf bound_ctrl:1\n\t"
;                 "s_nop 0\n\t"
;                 "v_add_f32_dpp %0, %0, %0 quad_perm:[2,3,0,1] row_mask:0xf bank_mask:0xf bound_ctrl:1\n\t"
;                 "v_add_f32_dpp %1, %1, %1 quad_perm:[2,3,0,1] row_mask:0xf bank_mask:0xf bound_ctrl:1\n\t"
;                 "s_nop 0\n\t"
;                 "v_add_f32_dpp %0, %0, %0 row_half_mirror row_mask:0xf bank_mask:0xf bound_ctrl:1\n\t"
;                 "v_add_f32_dpp %1, %1, %1 row_half_mirror row_mask:0xf bank_mask:0xf bound_ctrl:1"
;                 : "+v"(da), "+v"(dy));
;             {
;                 f32x2 t0;
;                 t0 = c[8].xy * v0; t0 = c[6].xy * da + t0; sp[0] = sp[0] * c[4].xy + t0;
;                 t0 = c[8].zw * v0; t0 = c[6].zw * da + t0; sp[1] = sp[1] * c[4].zw + t0;
;                 t0 = c[9].xy * v0; t0 = c[7].xy * da + t0; sp[2] = sp[2] * c[5].xy + t0;
;                 t0 = c[9].zw * v0; t0 = c[7].zw * da + t0; sp[3] = sp[3] * c[5].zw + t0;
;             }
;             ybb[t * 32] = dy + da * bk.x + v0 * bk.y;
;         }
	v_pk_mul_f32 v[122:123], v[38:39], v[42:43]
	v_pk_mul_f32 v[124:125], v[38:39], v[50:51]
	v_pk_fma_f32 v[122:123], v[36:37], v[40:41], v[122:123]
	v_pk_fma_f32 v[124:125], v[36:37], v[48:49], v[124:125]
	v_pk_fma_f32 v[122:123], v[32:33], v[44:45], v[122:123]
	v_pk_fma_f32 v[124:125], v[32:33], v[52:53], v[124:125]
	v_pk_fma_f32 v[122:123], v[34:35], v[46:47], v[122:123]
	v_pk_fma_f32 v[124:125], v[34:35], v[54:55], v[124:125]
	v_pk_mul_f32 v[126:127], v[72:73], v[94:95] op_sel_hi:[1,0]
	v_add_f32_e32 v166, v122, v123
	v_add_f32_e32 v168, v124, v125
	v_pk_mul_f32 v[128:129], v[74:75], v[94:95] op_sel_hi:[1,0]
	v_pk_mul_f32 v[130:131], v[76:77], v[94:95] op_sel_hi:[1,0]
	v_add_f32_dpp v166, v166, v166 quad_perm:[1,0,3,2] row_mask:0xf bank_mask:0xf bound_ctrl:1
	v_add_f32_dpp v168, v168, v168 quad_perm:[1,0,3,2] row_mask:0xf bank_mask:0xf bound_ctrl:1
	v_pk_mul_f32 v[132:133], v[78:79], v[94:95] op_sel_hi:[1,0]
	v_pk_fma_f32 v[126:127], v[36:37], v[56:57], v[126:127]
	v_add_f32_dpp v166, v166, v166 quad_perm:[2,3,0,1] row_mask:0xf bank_mask:0xf bound_ctrl:1
	v_add_f32_dpp v168, v168, v168 quad_perm:[2,3,0,1] row_mask:0xf bank_mask:0xf bound_ctrl:1
	v_pk_fma_f32 v[128:129], v[38:39], v[58:59], v[128:129]
	v_pk_fma_f32 v[130:131], v[32:33], v[60:61], v[130:131]
	v_add_f32_dpp v166, v166, v166 row_half_mirror row_mask:0xf bank_mask:0xf bound_ctrl:1
	v_add_f32_dpp v168, v168, v168 row_half_mirror row_mask:0xf bank_mask:0xf bound_ctrl:1
	v_pk_fma_f32 v[132:133], v[34:35], v[62:63], v[132:133]
	v_mov_b32_e32 v167, v94
	v_pk_mul_f32 v[134:135], v[166:167], v[108:109]
	v_pk_fma_f32 v[36:37], v[64:65], v[166:167], v[126:127] op_sel_hi:[1,0,1]
	v_pk_fma_f32 v[38:39], v[66:67], v[166:167], v[128:129] op_sel_hi:[1,0,1]
	v_pk_fma_f32 v[32:33], v[68:69], v[166:167], v[130:131] op_sel_hi:[1,0,1]
	v_pk_fma_f32 v[34:35], v[70:71], v[166:167], v[132:133] op_sel_hi:[1,0,1]
	v_add_f32_e32 v136, v168, v134
	v_add_f32_e32 v136, v135, v136
	ds_write_b32 v95, v136 offset:256
	ds_read_b128 v[40:43], v120 offset:5120
	ds_read_b128 v[44:47], v120 offset:5136
	ds_read_b128 v[48:51], v120 offset:5376
	ds_read_b128 v[52:55], v120 offset:5392
	ds_read_b128 v[56:59], v120 offset:5632
	ds_read_b128 v[60:63], v120 offset:5648
	ds_read_b128 v[64:67], v120 offset:5888
	ds_read_b128 v[68:71], v120 offset:5904
	ds_read_b128 v[72:75], v120 offset:6144
	ds_read_b128 v[76:79], v120 offset:6160
	ds_read_b32 v94, v96 offset:21504
	ds_read_b64 v[108:109], v121 offset:24640
	s_waitcnt lgkmcnt(12)
	v_pk_mul_f32 v[122:123], v[38:39], v[192:193]
	v_pk_mul_f32 v[124:125], v[38:39], v[200:201]
	v_pk_fma_f32 v[122:123], v[36:37], v[190:191], v[122:123]
	v_pk_fma_f32 v[124:125], v[36:37], v[198:199], v[124:125]
	v_pk_fma_f32 v[122:123], v[32:33], v[194:195], v[122:123]
	v_pk_fma_f32 v[124:125], v[32:33], v[202:203], v[124:125]
	v_pk_fma_f32 v[122:123], v[34:35], v[196:197], v[122:123]
	v_pk_fma_f32 v[124:125], v[34:35], v[204:205], v[124:125]
	v_pk_mul_f32 v[126:127], v[222:223], v[230:231] op_sel_hi:[1,0]
	v_add_f32_e32 v166, v122, v123
	v_add_f32_e32 v168, v124, v125
	v_pk_mul_f32 v[128:129], v[224:225], v[230:231] op_sel_hi:[1,0]
	v_pk_mul_f32 v[130:131], v[226:227], v[230:231] op_sel_hi:[1,0]
	v_add_f32_dpp v166, v166, v166 quad_perm:[1,0,3,2] row_mask:0xf bank_mask:0xf bound_ctrl:1
	v_add_f32_dpp v168, v168, v168 quad_perm:[1,0,3,2] row_mask:0xf bank_mask:0xf bound_ctrl:1
	v_pk_mul_f32 v[132:133], v[228:229], v[230:231] op_sel_hi:[1,0]
	v_pk_fma_f32 v[126:127], v[36:37], v[206:207], v[126:127]
	v_add_f32_dpp v166, v166, v166 quad_perm:[2,3,0,1] row_mask:0xf bank_mask:0xf bound_ctrl:1
	v_add_f32_dpp v168, v168, v168 quad_perm:[2,3,0,1] row_mask:0xf bank_mask:0xf bound_ctrl:1
	v_pk_fma_f32 v[128:129], v[38:39], v[208:209], v[128:129]
	v_pk_fma_f32 v[130:131], v[32:33], v[210:211], v[130:131]
	v_add_f32_dpp v166, v166, v166 row_half_mirror row_mask:0xf bank_mask:0xf bound_ctrl:1
	v_add_f32_dpp v168, v168, v168 row_half_mirror row_mask:0xf bank_mask:0xf bound_ctrl:1
	v_pk_fma_f32 v[132:133], v[34:35], v[212:213], v[132:133]
	v_mov_b32_e32 v167, v230
	v_pk_mul_f32 v[134:135], v[166:167], v[232:233]
	v_pk_fma_f32 v[36:37], v[214:215], v[166:167], v[126:127] op_sel_hi:[1,0,1]
	v_pk_fma_f32 v[38:39], v[216:217], v[166:167], v[128:129] op_sel_hi:[1,0,1]
	v_pk_fma_f32 v[32:33], v[218:219], v[166:167], v[130:131] op_sel_hi:[1,0,1]
	v_pk_fma_f32 v[34:35], v[220:221], v[166:167], v[132:133] op_sel_hi:[1,0,1]
	v_add_f32_e32 v136, v168, v134
	v_add_f32_e32 v136, v135, v136
	ds_write_b32 v95, v136 offset:384
	ds_read_b128 v[190:193], v120 offset:6400
	ds_read_b128 v[194:197], v120 offset:6416
	ds_read_b128 v[198:201], v120 offset:6656
	ds_read_b128 v[202:205], v120 offset:6672
	ds_read_b128 v[206:209], v120 offset:6912
	ds_read_b128 v[210:213], v120 offset:6928
	ds_read_b128 v[214:217], v120 offset:7168
	ds_read_b128 v[218:221], v120 offset:7184
	ds_read_b128 v[222:225], v120 offset:7424
	ds_read_b128 v[226:229], v120 offset:7440
	ds_read_b32 v230, v96 offset:21760
	ds_read_b64 v[232:233], v121 offset:24656
	s_waitcnt lgkmcnt(12)
; #define SC_LOAD(t) { _Pragma("unroll") for (int q = 0; q < 5; ++q) { n[2 * q] = *(const LAS f32x4*)(opb + (t) * 320 + q * 64); n[2 * q + 1] = *(const LAS f32x4*)(opb + (t) * 320 + q * 64 + 4); } \
;                      nv = vvb[(t) * 64]; nbk = *(const LAS f32x2*)(scb + (t) * 4); }
; DI void scan_item(const __attribute__((address_space(4))) Args& a, LAS unsigned char* lds, int ws_, bool is_prompt, int seq, int h, int half, bool dry = false) {
;     ...
;         SC_LOAD(0)
; #pragma unroll 4
;         for (int t = 0; t < SC_CH; ++t) {
;             f32x4 c[10];
; #pragma unroll
;             for (int q = 0; q < 10; ++q) c[q] = n[q];
;             const float v0 = nv; const f32x2 bk = nbk;
;             SC_LOAD(t + 1)
;             __builtin_amdgcn_sched_barrier(0);
;             f32x2 aA = sp[0] * c[0].xy, aY = sp[0] * c[2].xy;
;             aA = sp[1] * c[0].zw + aA; aY = sp[1] * c[2].zw + aY;
;             aA = sp[2] * c[1].xy + aA; aY = sp[2] * c[3].xy + aY;
;             aA = sp[3] * c[1].zw + aA; aY = sp[3] * c[3].zw + aY;
;             float da = aA.x + aA.y, dy = aY.x + aY.y;
;             asm("s_nop 1\n\t"
;                 "v_add_f32_dpp %0, %0, %0 quad_perm:[1,0,3,2] row_mask:0xf bank_mask:0xf bound_ctrl:1\n\t"
;                 "v_add_f32_dpp %1, %1, %1 quad_perm:[1,0,3,2] row_mask:0xf bank_mask:0xf bound_ctrl:1\n\t"
;                 "s_nop 0\n\t"
;                 "v_add_f32_dpp %0, %0, %0 quad_perm:[2,3,0,1] row_mask:0xf bank_mask:0xf bound_ctrl:1\n\t"
;                 "v_add_f32_dpp %1, %1, %1 quad_perm:[2,3,0,1] row_mask:0xf bank_mask:0xf bound_ctrl:1\n\t"
;                 "s_nop 0\n\t"
;                 "v_add_f32_dpp %0, %0, %0 row_half_mirror row_mask:0xf bank_mask:0xf bound_ctrl:1\n\t"
;                 "v_add_f32_dpp %1, %1, %1 row_half_mirror row_mask:0xf bank_mask:0xf bound_ctrl:1"
;                 : "+v"(da), "+v"(dy));
;             {
;                 f32x2 t0;
;                 t0 = c[8].xy * v0; t0 = c[6].xy * da + t0; sp[0] = sp[0] * c[4].xy + t0;
;                 t0 = c[8].zw * v0; t0 = c[6].zw * da + t0; sp[1] = sp[1] * c[4].zw + t0;
;                 t0 = c[9].xy * v0; t0 = c[7].xy * da + t0; sp[2] = sp[2] * c[5].xy + t0;
;                 t0 = c[9].zw * v0; t0 = c[7].zw * da + t0; sp[3] = sp[3] * c[5].zw + t0;
;             }
;             ybb[t * 32] = dy + da * bk.x + v0 * bk.y;
;         }
	v_pk_mul_f32 v[122:123], v[38:39], v[42:43]
	v_pk_mul_f32 v[124:125], v[38:39], v[50:51]
	v_pk_fma_f32 v[122:123], v[36:37], v[40:41], v[122:123]
	v_pk_fma_f32 v[124:125], v[36:37], v[48:49], v[124:125]
	v_pk_fma_f32 v[122:123], v[32:33], v[44:45], v[122:123]
	v_pk_fma_f32 v[124:125], v[32:33], v[52:53], v[124:125]
	v_pk_fma_f32 v[122:123], v[34:35], v[46:47], v[122:123]
	v_pk_fma_f32 v[124:125], v[34:35], v[54:55], v[124:125]
	v_pk_mul_f32 v[126:127], v[72:73], v[94:95] op_sel_hi:[1,0]
	v_add_f32_e32 v166, v122, v123
	v_add_f32_e32 v168, v124, v125
	v_pk_mul_f32 v[128:129], v[74:75], v[94:95] op_sel_hi:[1,0]
	v_pk_mul_f32 v[130:131], v[76:77], v[94:95] op_sel_hi:[1,0]
	v_add_f32_dpp v166, v166, v166 quad_perm:[1,0,3,2] row_mask:0xf bank_mask:0xf bound_ctrl:1
	v_add_f32_dpp v168, v168, v168 quad_perm:[1,0,3,2] row_mask:0xf bank_mask:0xf bound_ctrl:1
	v_pk_mul_f32 v[132:133], v[78:79], v[94:95] op_sel_hi:[1,0]
	v_pk_fma_f32 v[126:127], v[36:37], v[56:57], v[126:127]
	v_add_f32_dpp v166, v166, v166 quad_perm:[2,3,0,1] row_mask:0xf bank_mask:0xf bound_ctrl:1
	v_add_f32_dpp v168, v168, v168 quad_perm:[2,3,0,1] row_mask:0xf bank_mask:0xf bound_ctrl:1
	v_pk_fma_f32 v[128:129], v[38:39], v[58:59], v[128:129]
	v_pk_fma_f32 v[130:131], v[32:33], v[60:61], v[130:131]
	v_add_f32_dpp v166, v166, v166 row_half_mirror row_mask:0xf bank_mask:0xf bound_ctrl:1
	v_add_f32_dpp v168, v168, v168 row_half_mirror row_mask:0xf bank_mask:0xf bound_ctrl:1
	v_pk_fma_f32 v[132:133], v[34:35], v[62:63], v[132:133]
	v_mov_b32_e32 v167, v94
	v_pk_mul_f32 v[134:135], v[166:167], v[108:109]
	v_pk_fma_f32 v[36:37], v[64:65], v[166:167], v[126:127] op_sel_hi:[1,0,1]
	v_pk_fma_f32 v[38:39], v[66:67], v[166:167], v[128:129] op_sel_hi:[1,0,1]
	v_pk_fma_f32 v[32:33], v[68:69], v[166:167], v[130:131] op_sel_hi:[1,0,1]
	v_pk_fma_f32 v[34:35], v[70:71], v[166:167], v[132:133] op_sel_hi:[1,0,1]
	v_add_f32_e32 v136, v168, v134
	v_add_f32_e32 v136, v135, v136
	ds_write_b32 v95, v136 offset:512
	ds_read_b128 v[40:43], v120 offset:7680
	ds_read_b128 v[44:47], v120 offset:7696
	ds_read_b128 v[48:51], v120 offset:7936
	ds_read_b128 v[52:55], v120 offset:7952
	ds_read_b128 v[56:59], v120 offset:8192
	ds_read_b128 v[60:63], v120 offset:8208
	ds_read_b128 v[64:67], v120 offset:8448
	ds_read_b128 v[68:71], v120 offset:8464
	ds_read_b128 v[72:75], v120 offset:8704
	ds_read_b128 v[76:79], v120 offset:8720
	ds_read_b32 v94, v96 offset:22016
	ds_read_b64 v[108:109], v121 offset:24672
	s_waitcnt lgkmcnt(12)
	v_pk_mul_f32 v[122:123], v[38:39], v[192:193]
	v_pk_mul_f32 v[124:125], v[38:39], v[200:201]
	v_pk_fma_f32 v[122:123], v[36:37], v[190:191], v[122:123]
	v_pk_fma_f32 v[124:125], v[36:37], v[198:199], v[124:125]
	v_pk_fma_f32 v[122:123], v[32:33], v[194:195], v[122:123]
	v_pk_fma_f32 v[124:125], v[32:33], v[202:203], v[124:125]
	v_pk_fma_f32 v[122:123], v[34:35], v[196:197], v[122:123]
	v_pk_fma_f32 v[124:125], v[34:35], v[204:205], v[124:125]
	v_pk_mul_f32 v[126:127], v[222:223], v[230:231] op_sel_hi:[1,0]
	v_add_f32_e32 v166, v122, v123
	v_add_f32_e32 v168, v124, v125
	v_pk_mul_f32 v[128:129], v[224:225], v[230:231] op_sel_hi:[1,0]
	v_pk_mul_f32 v[130:131], v[226:227], v[230:231] op_sel_hi:[1,0]
	v_add_f32_dpp v166, v166, v166 quad_perm:[1,0,3,2] row_mask:0xf bank_mask:0xf bound_ctrl:1
	v_add_f32_dpp v168, v168, v168 quad_perm:[1,0,3,2] row_mask:0xf bank_mask:0xf bound_ctrl:1
	v_pk_mul_f32 v[132:133], v[228:229], v[230:231] op_sel_hi:[1,0]
	v_pk_fma_f32 v[126:127], v[36:37], v[206:207], v[126:127]
	v_add_f32_dpp v166, v166, v166 quad_perm:[2,3,0,1] row_mask:0xf bank_mask:0xf bound_ctrl:1
	v_add_f32_dpp v168, v168, v168 quad_perm:[2,3,0,1] row_mask:0xf bank_mask:0xf bound_ctrl:1
	v_pk_fma_f32 v[128:129], v[38:39], v[208:209], v[128:129]
	v_pk_fma_f32 v[130:131], v[32:33], v[210:211], v[130:131]
	v_add_f32_dpp v166, v166, v166 row_half_mirror row_mask:0xf bank_mask:0xf bound_ctrl:1
	v_add_f32_dpp v168, v168, v168 row_half_mirror row_mask:0xf bank_mask:0xf bound_ctrl:1
	v_pk_fma_f32 v[132:133], v[34:35], v[212:213], v[132:133]
	v_mov_b32_e32 v167, v230
	v_pk_mul_f32 v[134:135], v[166:167], v[232:233]
	v_pk_fma_f32 v[36:37], v[214:215], v[166:167], v[126:127] op_sel_hi:[1,0,1]
	v_pk_fma_f32 v[38:39], v[216:217], v[166:167], v[128:129] op_sel_hi:[1,0,1]
	v_pk_fma_f32 v[32:33], v[218:219], v[166:167], v[130:131] op_sel_hi:[1,0,1]
	v_pk_fma_f32 v[34:35], v[220:221], v[166:167], v[132:133] op_sel_hi:[1,0,1]
	v_add_f32_e32 v136, v168, v134
	v_add_f32_e32 v136, v135, v136
	ds_write_b32 v95, v136 offset:640
	ds_read_b128 v[190:193], v120 offset:8960
	ds_read_b128 v[194:197], v120 offset:8976
	ds_read_b128 v[198:201], v120 offset:9216
	ds_read_b128 v[202:205], v120 offset:9232
	ds_read_b128 v[206:209], v120 offset:9472
	ds_read_b128 v[210:213], v120 offset:9488
	ds_read_b128 v[214:217], v120 offset:9728
	ds_read_b128 v[218:221], v120 offset:9744
	ds_read_b128 v[222:225], v120 offset:9984
	ds_read_b128 v[226:229], v120 offset:10000
	ds_read_b32 v230, v96 offset:22272
	ds_read_b64 v[232:233], v121 offset:24688
	s_waitcnt lgkmcnt(12)
; #define SC_LOAD(t) { _Pragma("unroll") for (int q = 0; q < 5; ++q) { n[2 * q] = *(const LAS f32x4*)(opb + (t) * 320 + q * 64); n[2 * q + 1] = *(const LAS f32x4*)(opb + (t) * 320 + q * 64 + 4); } \
;                      nv = vvb[(t) * 64]; nbk = *(const LAS f32x2*)(scb + (t) * 4); }
; DI void scan_item(const __attribute__((address_space(4))) Args& a, LAS unsigned char* lds, int ws_, bool is_prompt, int seq, int h, int half, bool dry = false) {
;     ...
;         SC_LOAD(0)
; #pragma unroll 4
;         for (int t = 0; t < SC_CH; ++t) {
;             f32x4 c[10];
; #pragma unroll
;             for (int q = 0; q < 10; ++q) c[q] = n[q];
;             const float v0 = nv; const f32x2 bk = nbk;
;             SC_LOAD(t + 1)
;             __builtin_amdgcn_sched_barrier(0);
;             f32x2 aA = sp[0] * c[0].xy, aY = sp[0] * c[2].xy;
;             aA = sp[1] * c[0].zw + aA; aY = sp[1] * c[2].zw + aY;
;             aA = sp[2] * c[1].xy + aA; aY = sp[2] * c[3].xy + aY;
;             aA = sp[3] * c[1].zw + aA; aY = sp[3] * c[3].zw + aY;
;             float da = aA.x + aA.y, dy = aY.x + aY.y;
;             asm("s_nop 1\n\t"
;                 "v_add_f32_dpp %0, %0, %0 quad_perm:[1,0,3,2] row_mask:0xf bank_mask:0xf bound_ctrl:1\n\t"
;                 "v_add_f32_dpp %1, %1, %1 quad_perm:[1,0,3,2] row_mask:0xf bank_mask:0xf bound_ctrl:1\n\t"
;                 "s_nop 0\n\t"
;                 "v_add_f32_dpp %0, %0, %0 quad_perm:[2,3,0,1] row_mask:0xf bank_mask:0xf bound_ctrl:1\n\t"
;                 "v_add_f32_dpp %1, %1, %1 quad_perm:[2,3,0,1] row_mask:0xf bank_mask:0xf bound_ctrl:1\n\t"
;                 "s_nop 0\n\t"
;                 "v_add_f32_dpp %0, %0, %0 row_half_mirror row_mask:0xf bank_mask:0xf bound_ctrl:1\n\t"
;                 "v_add_f32_dpp %1, %1, %1 row_half_mirror row_mask:0xf bank_mask:0xf bound_ctrl:1"
;                 : "+v"(da), "+v"(dy));
;             {
;                 f32x2 t0;
;                 t0 = c[8].xy * v0; t0 = c[6].xy * da + t0; sp[0] = sp[0] * c[4].xy + t0;
;                 t0 = c[8].zw * v0; t0 = c[6].zw * da + t0; sp[1] = sp[1] * c[4].zw + t0;
;                 t0 = c[9].xy * v0; t0 = c[7].xy * da + t0; sp[2] = sp[2] * c[5].xy + t0;
;                 t0 = c[9].zw * v0; t0 = c[7].zw * da + t0; sp[3] = sp[3] * c[5].zw + t0;
;             }
;             ybb[t * 32] = dy + da * bk.x + v0 * bk.y;
;         }
	v_pk_mul_f32 v[122:123], v[38:39], v[42:43]
	v_pk_mul_f32 v[124:125], v[38:39], v[50:51]
	v_pk_fma_f32 v[122:123], v[36:37], v[40:41], v[122:123]
	v_pk_fma_f32 v[124:125], v[36:37], v[48:49], v[124:125]
	v_pk_fma_f32 v[122:123], v[32:33], v[44:45], v[122:123]
	v_pk_fma_f32 v[124:125], v[32:33], v[52:53], v[124:125]
	v_pk_fma_f32 v[122:123], v[34:35], v[46:47], v[122:123]
	v_pk_fma_f32 v[124:125], v[34:35], v[54:55], v[124:125]
	v_pk_mul_f32 v[126:127], v[72:73], v[94:95] op_sel_hi:[1,0]
	v_add_f32_e32 v166, v122, v123
	v_add_f32_e32 v168, v124, v125
	v_pk_mul_f32 v[128:129], v[74:75], v[94:95] op_sel_hi:[1,0]
	v_pk_mul_f32 v[130:131], v[76:77], v[94:95] op_sel_hi:[1,0]
	v_add_f32_dpp v166, v166, v166 quad_perm:[1,0,3,2] row_mask:0xf bank_mask:0xf bound_ctrl:1
	v_add_f32_dpp v168, v168, v168 quad_perm:[1,0,3,2] row_mask:0xf bank_mask:0xf bound_ctrl:1
	v_pk_mul_f32 v[132:133], v[78:79], v[94:95] op_sel_hi:[1,0]
	v_pk_fma_f32 v[126:127], v[36:37], v[56:57], v[126:127]
	v_add_f32_dpp v166, v166, v166 quad_perm:[2,3,0,1] row_mask:0xf bank_mask:0xf bound_ctrl:1
	v_add_f32_dpp v168, v168, v168 quad_perm:[2,3,0,1] row_mask:0xf bank_mask:0xf bound_ctrl:1
	v_pk_fma_f32 v[128:129], v[38:39], v[58:59], v[128:129]
	v_pk_fma_f32 v[130:131], v[32:33], v[60:61], v[130:131]
	v_add_f32_dpp v166, v166, v166 row_half_mirror row_mask:0xf bank_mask:0xf bound_ctrl:1
	v_add_f32_dpp v168, v168, v168 row_half_mirror row_mask:0xf bank_mask:0xf bound_ctrl:1
	v_pk_fma_f32 v[132:133], v[34:35], v[62:63], v[132:133]
	v_mov_b32_e32 v167, v94
	v_pk_mul_f32 v[134:135], v[166:167], v[108:109]
	v_pk_fma_f32 v[36:37], v[64:65], v[166:167], v[126:127] op_sel_hi:[1,0,1]
	v_pk_fma_f32 v[38:39], v[66:67], v[166:167], v[128:129] op_sel_hi:[1,0,1]
	v_pk_fma_f32 v[32:33], v[68:69], v[166:167], v[130:131] op_sel_hi:[1,0,1]
	v_pk_fma_f32 v[34:35], v[70:71], v[166:167], v[132:133] op_sel_hi:[1,0,1]
	v_add_f32_e32 v136, v168, v134
	v_add_f32_e32 v136, v135, v136
	ds_write_b32 v95, v136 offset:768
	ds_read_b128 v[40:43], v120 offset:10240
	ds_read_b128 v[44:47], v120 offset:10256
	ds_read_b128 v[48:51], v120 offset:10496
	ds_read_b128 v[52:55], v120 offset:10512
	ds_read_b128 v[56:59], v120 offset:10752
	ds_read_b128 v[60:63], v120 offset:10768
	ds_read_b128 v[64:67], v120 offset:11008
	ds_read_b128 v[68:71], v120 offset:11024
	ds_read_b128 v[72:75], v120 offset:11264
	ds_read_b128 v[76:79], v120 offset:11280
	ds_read_b32 v94, v96 offset:22528
	ds_read_b64 v[108:109], v121 offset:24704
	s_waitcnt lgkmcnt(12)
	v_pk_mul_f32 v[122:123], v[38:39], v[192:193]
	v_pk_mul_f32 v[124:125], v[38:39], v[200:201]
	v_pk_fma_f32 v[122:123], v[36:37], v[190:191], v[122:123]
	v_pk_fma_f32 v[124:125], v[36:37], v[198:199], v[124:125]
	v_pk_fma_f32 v[122:123], v[32:33], v[194:195], v[122:123]
	v_pk_fma_f32 v[124:125], v[32:33], v[202:203], v[124:125]
	v_pk_fma_f32 v[122:123], v[34:35], v[196:197], v[122:123]
	v_pk_fma_f32 v[124:125], v[34:35], v[204:205], v[124:125]
	v_pk_mul_f32 v[126:127], v[222:223], v[230:231] op_sel_hi:[1,0]
	v_add_f32_e32 v166, v122, v123
	v_add_f32_e32 v168, v124, v125
	v_pk_mul_f32 v[128:129], v[224:225], v[230:231] op_sel_hi:[1,0]
	v_pk_mul_f32 v[130:131], v[226:227], v[230:231] op_sel_hi:[1,0]
	v_add_f32_dpp v166, v166, v166 quad_perm:[1,0,3,2] row_mask:0xf bank_mask:0xf bound_ctrl:1
	v_add_f32_dpp v168, v168, v168 quad_perm:[1,0,3,2] row_mask:0xf bank_mask:0xf bound_ctrl:1
	v_pk_mul_f32 v[132:133], v[228:229], v[230:231] op_sel_hi:[1,0]
	v_pk_fma_f32 v[126:127], v[36:37], v[206:207], v[126:127]
	v_add_f32_dpp v166, v166, v166 quad_perm:[2,3,0,1] row_mask:0xf bank_mask:0xf bound_ctrl:1
	v_add_f32_dpp v168, v168, v168 quad_perm:[2,3,0,1] row_mask:0xf bank_mask:0xf bound_ctrl:1
	v_pk_fma_f32 v[128:129], v[38:39], v[208:209], v[128:129]
	v_pk_fma_f32 v[130:131], v[32:33], v[210:211], v[130:131]
	v_add_f32_dpp v166, v166, v166 row_half_mirror row_mask:0xf bank_mask:0xf bound_ctrl:1
	v_add_f32_dpp v168, v168, v168 row_half_mirror row_mask:0xf bank_mask:0xf bound_ctrl:1
	v_pk_fma_f32 v[132:133], v[34:35], v[212:213], v[132:133]
	v_mov_b32_e32 v167, v230
	v_pk_mul_f32 v[134:135], v[166:167], v[232:233]
	v_pk_fma_f32 v[36:37], v[214:215], v[166:167], v[126:127] op_sel_hi:[1,0,1]
	v_pk_fma_f32 v[38:39], v[216:217], v[166:167], v[128:129] op_sel_hi:[1,0,1]
	v_pk_fma_f32 v[32:33], v[218:219], v[166:167], v[130:131] op_sel_hi:[1,0,1]
	v_pk_fma_f32 v[34:35], v[220:221], v[166:167], v[132:133] op_sel_hi:[1,0,1]
	v_add_f32_e32 v136, v168, v134
	v_add_f32_e32 v136, v135, v136
	ds_write_b32 v95, v136 offset:896
	ds_read_b128 v[190:193], v120 offset:11520
	ds_read_b128 v[194:197], v120 offset:11536
	ds_read_b128 v[198:201], v120 offset:11776
	ds_read_b128 v[202:205], v120 offset:11792
	ds_read_b128 v[206:209], v120 offset:12032
	ds_read_b128 v[210:213], v120 offset:12048
	ds_read_b128 v[214:217], v120 offset:12288
	ds_read_b128 v[218:221], v120 offset:12304
	ds_read_b128 v[222:225], v120 offset:12544
	ds_read_b128 v[226:229], v120 offset:12560
	ds_read_b32 v230, v96 offset:22784
	ds_read_b64 v[232:233], v121 offset:24720
	s_waitcnt lgkmcnt(12)
; #define SC_LOAD(t) { _Pragma("unroll") for (int q = 0; q < 5; ++q) { n[2 * q] = *(const LAS f32x4*)(opb + (t) * 320 + q * 64); n[2 * q + 1] = *(const LAS f32x4*)(opb + (t) * 320 + q * 64 + 4); } \
;                      nv = vvb[(t) * 64]; nbk = *(const LAS f32x2*)(scb + (t) * 4); }
; DI void scan_item(const __attribute__((address_space(4))) Args& a, LAS unsigned char* lds, int ws_, bool is_prompt, int seq, int h, int half, bool dry = false) {
;     ...
;         SC_LOAD(0)
; #pragma unroll 4
;         for (int t = 0; t < SC_CH; ++t) {
;             f32x4 c[10];
; #pragma unroll
;             for (int q = 0; q < 10; ++q) c[q] = n[q];
;             const float v0 = nv; const f32x2 bk = nbk;
;             SC_LOAD(t + 1)
;             __builtin_amdgcn_sched_barrier(0);
;             f32x2 aA = sp[0] * c[0].xy, aY = sp[0] * c[2].xy;
;             aA = sp[1] * c[0].zw + aA; aY = sp[1] * c[2].zw + aY;
;             aA = sp[2] * c[1].xy + aA; aY = sp[2] * c[3].xy + aY;
;             aA = sp[3] * c[1].zw + aA; aY = sp[3] * c[3].zw + aY;
;             float da = aA.x + aA.y, dy = aY.x + aY.y;
;             asm("s_nop 1\n\t"
;                 "v_add_f32_dpp %0, %0, %0 quad_perm:[1,0,3,2] row_mask:0xf bank_mask:0xf bound_ctrl:1\n\t"
;                 "v_add_f32_dpp %1, %1, %1 quad_perm:[1,0,3,2] row_mask:0xf bank_mask:0xf bound_ctrl:1\n\t"
;                 "s_nop 0\n\t"
;                 "v_add_f32_dpp %0, %0, %0 quad_perm:[2,3,0,1] row_mask:0xf bank_mask:0xf bound_ctrl:1\n\t"
;                 "v_add_f32_dpp %1, %1, %1 quad_perm:[2,3,0,1] row_mask:0xf bank_mask:0xf bound_ctrl:1\n\t"
;                 "s_nop 0\n\t"
;                 "v_add_f32_dpp %0, %0, %0 row_half_mirror row_mask:0xf bank_mask:0xf bound_ctrl:1\n\t"
;                 "v_add_f32_dpp %1, %1, %1 row_half_mirror row_mask:0xf bank_mask:0xf bound_ctrl:1"
;                 : "+v"(da), "+v"(dy));
;             {
;                 f32x2 t0;
;                 t0 = c[8].xy * v0; t0 = c[6].xy * da + t0; sp[0] = sp[0] * c[4].xy + t0;
;                 t0 = c[8].zw * v0; t0 = c[6].zw * da + t0; sp[1] = sp[1] * c[4].zw + t0;
;                 t0 = c[9].xy * v0; t0 = c[7].xy * da + t0; sp[2] = sp[2] * c[5].xy + t0;
;                 t0 = c[9].zw * v0; t0 = c[7].zw * da + t0; sp[3] = sp[3] * c[5].zw + t0;
;             }
;             ybb[t * 32] = dy + da * bk.x + v0 * bk.y;
;         }
	v_pk_mul_f32 v[122:123], v[38:39], v[42:43]
	v_pk_mul_f32 v[124:125], v[38:39], v[50:51]
	v_pk_fma_f32 v[122:123], v[36:37], v[40:41], v[122:123]
	v_pk_fma_f32 v[124:125], v[36:37], v[48:49], v[124:125]
	v_pk_fma_f32 v[122:123], v[32:33], v[44:45], v[122:123]
	v_pk_fma_f32 v[124:125], v[32:33], v[52:53], v[124:125]
	v_pk_fma_f32 v[122:123], v[34:35], v[46:47], v[122:123]
	v_pk_fma_f32 v[124:125], v[34:35], v[54:55], v[124:125]
	v_pk_mul_f32 v[126:127], v[72:73], v[94:95] op_sel_hi:[1,0]
	v_add_f32_e32 v166, v122, v123
	v_add_f32_e32 v168, v124, v125
	v_pk_mul_f32 v[128:129], v[74:75], v[94:95] op_sel_hi:[1,0]
	v_pk_mul_f32 v[130:131], v[76:77], v[94:95] op_sel_hi:[1,0]
	v_add_f32_dpp v166, v166, v166 quad_perm:[1,0,3,2] row_mask:0xf bank_mask:0xf bound_ctrl:1
	v_add_f32_dpp v168, v168, v168 quad_perm:[1,0,3,2] row_mask:0xf bank_mask:0xf bound_ctrl:1
	v_pk_mul_f32 v[132:133], v[78:79], v[94:95] op_sel_hi:[1,0]
	v_pk_fma_f32 v[126:127], v[36:37], v[56:57], v[126:127]
	v_add_f32_dpp v166, v166, v166 quad_perm:[2,3,0,1] row_mask:0xf bank_mask:0xf bound_ctrl:1
	v_add_f32_dpp v168, v168, v168 quad_perm:[2,3,0,1] row_mask:0xf bank_mask:0xf bound_ctrl:1
	v_pk_fma_f32 v[128:129], v[38:39], v[58:59], v[128:129]
	v_pk_fma_f32 v[130:131], v[32:33], v[60:61], v[130:131]
	v_add_f32_dpp v166, v166, v166 row_half_mirror row_mask:0xf bank_mask:0xf bound_ctrl:1
	v_add_f32_dpp v168, v168, v168 row_half_mirror row_mask:0xf bank_mask:0xf bound_ctrl:1
	v_pk_fma_f32 v[132:133], v[34:35], v[62:63], v[132:133]
	v_mov_b32_e32 v167, v94
	v_pk_mul_f32 v[134:135], v[166:167], v[108:109]
	v_pk_fma_f32 v[36:37], v[64:65], v[166:167], v[126:127] op_sel_hi:[1,0,1]
	v_pk_fma_f32 v[38:39], v[66:67], v[166:167], v[128:129] op_sel_hi:[1,0,1]
	v_pk_fma_f32 v[32:33], v[68:69], v[166:167], v[130:131] op_sel_hi:[1,0,1]
	v_pk_fma_f32 v[34:35], v[70:71], v[166:167], v[132:133] op_sel_hi:[1,0,1]
	v_add_f32_e32 v136, v168, v134
	v_add_f32_e32 v136, v135, v136
	ds_write_b32 v95, v136 offset:1024
	ds_read_b128 v[40:43], v120 offset:12800
	ds_read_b128 v[44:47], v120 offset:12816
	ds_read_b128 v[48:51], v120 offset:13056
	ds_read_b128 v[52:55], v120 offset:13072
	ds_read_b128 v[56:59], v120 offset:13312
	ds_read_b128 v[60:63], v120 offset:13328
	ds_read_b128 v[64:67], v120 offset:13568
	ds_read_b128 v[68:71], v120 offset:13584
	ds_read_b128 v[72:75], v120 offset:13824
	ds_read_b128 v[76:79], v120 offset:13840
	ds_read_b32 v94, v96 offset:23040
	ds_read_b64 v[108:109], v121 offset:24736
	s_waitcnt lgkmcnt(12)
	v_pk_mul_f32 v[122:123], v[38:39], v[192:193]
	v_pk_mul_f32 v[124:125], v[38:39], v[200:201]
	v_pk_fma_f32 v[122:123], v[36:37], v[190:191], v[122:123]
	v_pk_fma_f32 v[124:125], v[36:37], v[198:199], v[124:125]
	v_pk_fma_f32 v[122:123], v[32:33], v[194:195], v[122:123]
	v_pk_fma_f32 v[124:125], v[32:33], v[202:203], v[124:125]
	v_pk_fma_f32 v[122:123], v[34:35], v[196:197], v[122:123]
	v_pk_fma_f32 v[124:125], v[34:35], v[204:205], v[124:125]
	v_pk_mul_f32 v[126:127], v[222:223], v[230:231] op_sel_hi:[1,0]
	v_add_f32_e32 v166, v122, v123
	v_add_f32_e32 v168, v124, v125
	v_pk_mul_f32 v[128:129], v[224:225], v[230:231] op_sel_hi:[1,0]
	v_pk_mul_f32 v[130:131], v[226:227], v[230:231] op_sel_hi:[1,0]
	v_add_f32_dpp v166, v166, v166 quad_perm:[1,0,3,2] row_mask:0xf bank_mask:0xf bound_ctrl:1
	v_add_f32_dpp v168, v168, v168 quad_perm:[1,0,3,2] row_mask:0xf bank_mask:0xf bound_ctrl:1
	v_pk_mul_f32 v[132:133], v[228:229], v[230:231] op_sel_hi:[1,0]
	v_pk_fma_f32 v[126:127], v[36:37], v[206:207], v[126:127]
	v_add_f32_dpp v166, v166, v166 quad_perm:[2,3,0,1] row_mask:0xf bank_mask:0xf bound_ctrl:1
	v_add_f32_dpp v168, v168, v168 quad_perm:[2,3,0,1] row_mask:0xf bank_mask:0xf bound_ctrl:1
	v_pk_fma_f32 v[128:129], v[38:39], v[208:209], v[128:129]
	v_pk_fma_f32 v[130:131], v[32:33], v[210:211], v[130:131]
	v_add_f32_dpp v166, v166, v166 row_half_mirror row_mask:0xf bank_mask:0xf bound_ctrl:1
	v_add_f32_dpp v168, v168, v168 row_half_mirror row_mask:0xf bank_mask:0xf bound_ctrl:1
	v_pk_fma_f32 v[132:133], v[34:35], v[212:213], v[132:133]
	v_mov_b32_e32 v167, v230
	v_pk_mul_f32 v[134:135], v[166:167], v[232:233]
	v_pk_fma_f32 v[36:37], v[214:215], v[166:167], v[126:127] op_sel_hi:[1,0,1]
	v_pk_fma_f32 v[38:39], v[216:217], v[166:167], v[128:129] op_sel_hi:[1,0,1]
	v_pk_fma_f32 v[32:33], v[218:219], v[166:167], v[130:131] op_sel_hi:[1,0,1]
	v_pk_fma_f32 v[34:35], v[220:221], v[166:167], v[132:133] op_sel_hi:[1,0,1]
	v_add_f32_e32 v136, v168, v134
	v_add_f32_e32 v136, v135, v136
	ds_write_b32 v95, v136 offset:1152
	ds_read_b128 v[190:193], v120 offset:14080
	ds_read_b128 v[194:197], v120 offset:14096
	ds_read_b128 v[198:201], v120 offset:14336
	ds_read_b128 v[202:205], v120 offset:14352
	ds_read_b128 v[206:209], v120 offset:14592
	ds_read_b128 v[210:213], v120 offset:14608
	ds_read_b128 v[214:217], v120 offset:14848
	ds_read_b128 v[218:221], v120 offset:14864
	ds_read_b128 v[222:225], v120 offset:15104
	ds_read_b128 v[226:229], v120 offset:15120
	ds_read_b32 v230, v96 offset:23296
	ds_read_b64 v[232:233], v121 offset:24752
	s_waitcnt lgkmcnt(12)
; #define SC_LOAD(t) { _Pragma("unroll") for (int q = 0; q < 5; ++q) { n[2 * q] = *(const LAS f32x4*)(opb + (t) * 320 + q * 64); n[2 * q + 1] = *(const LAS f32x4*)(opb + (t) * 320 + q * 64 + 4); } \
;                      nv = vvb[(t) * 64]; nbk = *(const LAS f32x2*)(scb + (t) * 4); }
; DI void scan_item(const __attribute__((address_space(4))) Args& a, LAS unsigned char* lds, int ws_, bool is_prompt, int seq, int h, int half, bool dry = false) {
;     ...
;         SC_LOAD(0)
; #pragma unroll 4
;         for (int t = 0; t < SC_CH; ++t) {
;             f32x4 c[10];
; #pragma unroll
;             for (int q = 0; q < 10; ++q) c[q] = n[q];
;             const float v0 = nv; const f32x2 bk = nbk;
;             SC_LOAD(t + 1)
;             __builtin_amdgcn_sched_barrier(0);
;             f32x2 aA = sp[0] * c[0].xy, aY = sp[0] * c[2].xy;
;             aA = sp[1] * c[0].zw + aA; aY = sp[1] * c[2].zw + aY;
;             aA = sp[2] * c[1].xy + aA; aY = sp[2] * c[3].xy + aY;
;             aA = sp[3] * c[1].zw + aA; aY = sp[3] * c[3].zw + aY;
;             float da = aA.x + aA.y, dy = aY.x + aY.y;
;             asm("s_nop 1\n\t"
;                 "v_add_f32_dpp %0, %0, %0 quad_perm:[1,0,3,2] row_mask:0xf bank_mask:0xf bound_ctrl:1\n\t"
;                 "v_add_f32_dpp %1, %1, %1 quad_perm:[1,0,3,2] row_mask:0xf bank_mask:0xf bound_ctrl:1\n\t"
;                 "s_nop 0\n\t"
;                 "v_add_f32_dpp %0, %0, %0 quad_perm:[2,3,0,1] row_mask:0xf bank_mask:0xf bound_ctrl:1\n\t"
;                 "v_add_f32_dpp %1, %1, %1 quad_perm:[2,3,0,1] row_mask:0xf bank_mask:0xf bound_ctrl:1\n\t"
;                 "s_nop 0\n\t"
;                 "v_add_f32_dpp %0, %0, %0 row_half_mirror row_mask:0xf bank_mask:0xf bound_ctrl:1\n\t"
;                 "v_add_f32_dpp %1, %1, %1 row_half_mirror row_mask:0xf bank_mask:0xf bound_ctrl:1"
;                 : "+v"(da), "+v"(dy));
;             {
;                 f32x2 t0;
;                 t0 = c[8].xy * v0; t0 = c[6].xy * da + t0; sp[0] = sp[0] * c[4].xy + t0;
;                 t0 = c[8].zw * v0; t0 = c[6].zw * da + t0; sp[1] = sp[1] * c[4].zw + t0;
;                 t0 = c[9].xy * v0; t0 = c[7].xy * da + t0; sp[2] = sp[2] * c[5].xy + t0;
;                 t0 = c[9].zw * v0; t0 = c[7].zw * da + t0; sp[3] = sp[3] * c[5].zw + t0;
;             }
;             ybb[t * 32] = dy + da * bk.x + v0 * bk.y;
;         }
	v_pk_mul_f32 v[122:123], v[38:39], v[42:43]
	v_pk_mul_f32 v[124:125], v[38:39], v[50:51]
	v_pk_fma_f32 v[122:123], v[36:37], v[40:41], v[122:123]
	v_pk_fma_f32 v[124:125], v[36:37], v[48:49], v[124:125]
	v_pk_fma_f32 v[122:123], v[32:33], v[44:45], v[122:123]
	v_pk_fma_f32 v[124:125], v[32:33], v[52:53], v[124:125]
	v_pk_fma_f32 v[122:123], v[34:35], v[46:47], v[122:123]
	v_pk_fma_f32 v[124:125], v[34:35], v[54:55], v[124:125]
	v_pk_mul_f32 v[126:127], v[72:73], v[94:95] op_sel_hi:[1,0]
	v_add_f32_e32 v166, v122, v123
	v_add_f32_e32 v168, v124, v125
	v_pk_mul_f32 v[128:129], v[74:75], v[94:95] op_sel_hi:[1,0]
	v_pk_mul_f32 v[130:131], v[76:77], v[94:95] op_sel_hi:[1,0]
	v_add_f32_dpp v166, v166, v166 quad_perm:[1,0,3,2] row_mask:0xf bank_mask:0xf bound_ctrl:1
	v_add_f32_dpp v168, v168, v168 quad_perm:[1,0,3,2] row_mask:0xf bank_mask:0xf bound_ctrl:1
	v_pk_mul_f32 v[132:133], v[78:79], v[94:95] op_sel_hi:[1,0]
	v_pk_fma_f32 v[126:127], v[36:37], v[56:57], v[126:127]
	v_add_f32_dpp v166, v166, v166 quad_perm:[2,3,0,1] row_mask:0xf bank_mask:0xf bound_ctrl:1
	v_add_f32_dpp v168, v168, v168 quad_perm:[2,3,0,1] row_mask:0xf bank_mask:0xf bound_ctrl:1
	v_pk_fma_f32 v[128:129], v[38:39], v[58:59], v[128:129]
	v_pk_fma_f32 v[130:131], v[32:33], v[60:61], v[130:131]
	v_add_f32_dpp v166, v166, v166 row_half_mirror row_mask:0xf bank_mask:0xf bound_ctrl:1
	v_add_f32_dpp v168, v168, v168 row_half_mirror row_mask:0xf bank_mask:0xf bound_ctrl:1
	v_pk_fma_f32 v[132:133], v[34:35], v[62:63], v[132:133]
	v_mov_b32_e32 v167, v94
	v_pk_mul_f32 v[134:135], v[166:167], v[108:109]
	v_pk_fma_f32 v[36:37], v[64:65], v[166:167], v[126:127] op_sel_hi:[1,0,1]
	v_pk_fma_f32 v[38:39], v[66:67], v[166:167], v[128:129] op_sel_hi:[1,0,1]
	v_pk_fma_f32 v[32:33], v[68:69], v[166:167], v[130:131] op_sel_hi:[1,0,1]
	v_pk_fma_f32 v[34:35], v[70:71], v[166:167], v[132:133] op_sel_hi:[1,0,1]
	v_add_f32_e32 v136, v168, v134
	v_add_f32_e32 v136, v135, v136
	ds_write_b32 v95, v136 offset:1280
	ds_read_b128 v[40:43], v120 offset:15360
	ds_read_b128 v[44:47], v120 offset:15376
	ds_read_b128 v[48:51], v120 offset:15616
	ds_read_b128 v[52:55], v120 offset:15632
	ds_read_b128 v[56:59], v120 offset:15872
	ds_read_b128 v[60:63], v120 offset:15888
	ds_read_b128 v[64:67], v120 offset:16128
	ds_read_b128 v[68:71], v120 offset:16144
	ds_read_b128 v[72:75], v120 offset:16384
	ds_read_b128 v[76:79], v120 offset:16400
	ds_read_b32 v94, v96 offset:23552
	ds_read_b64 v[108:109], v121 offset:24768
	s_waitcnt lgkmcnt(12)
	v_pk_mul_f32 v[122:123], v[38:39], v[192:193]
	v_pk_mul_f32 v[124:125], v[38:39], v[200:201]
	v_pk_fma_f32 v[122:123], v[36:37], v[190:191], v[122:123]
	v_pk_fma_f32 v[124:125], v[36:37], v[198:199], v[124:125]
	v_pk_fma_f32 v[122:123], v[32:33], v[194:195], v[122:123]
	v_pk_fma_f32 v[124:125], v[32:33], v[202:203], v[124:125]
	v_pk_fma_f32 v[122:123], v[34:35], v[196:197], v[122:123]
	v_pk_fma_f32 v[124:125], v[34:35], v[204:205], v[124:125]
	v_pk_mul_f32 v[126:127], v[222:223], v[230:231] op_sel_hi:[1,0]
	v_add_f32_e32 v166, v122, v123
	v_add_f32_e32 v168, v124, v125
	v_pk_mul_f32 v[128:129], v[224:225], v[230:231] op_sel_hi:[1,0]
	v_pk_mul_f32 v[130:131], v[226:227], v[230:231] op_sel_hi:[1,0]
	v_add_f32_dpp v166, v166, v166 quad_perm:[1,0,3,2] row_mask:0xf bank_mask:0xf bound_ctrl:1
	v_add_f32_dpp v168, v168, v168 quad_perm:[1,0,3,2] row_mask:0xf bank_mask:0xf bound_ctrl:1
	v_pk_mul_f32 v[132:133], v[228:229], v[230:231] op_sel_hi:[1,0]
	v_pk_fma_f32 v[126:127], v[36:37], v[206:207], v[126:127]
	v_add_f32_dpp v166, v166, v166 quad_perm:[2,3,0,1] row_mask:0xf bank_mask:0xf bound_ctrl:1
	v_add_f32_dpp v168, v168, v168 quad_perm:[2,3,0,1] row_mask:0xf bank_mask:0xf bound_ctrl:1
	v_pk_fma_f32 v[128:129], v[38:39], v[208:209], v[128:129]
	v_pk_fma_f32 v[130:131], v[32:33], v[210:211], v[130:131]
	v_add_f32_dpp v166, v166, v166 row_half_mirror row_mask:0xf bank_mask:0xf bound_ctrl:1
	v_add_f32_dpp v168, v168, v168 row_half_mirror row_mask:0xf bank_mask:0xf bound_ctrl:1
	v_pk_fma_f32 v[132:133], v[34:35], v[212:213], v[132:133]
	v_mov_b32_e32 v167, v230
	v_pk_mul_f32 v[134:135], v[166:167], v[232:233]
	v_pk_fma_f32 v[36:37], v[214:215], v[166:167], v[126:127] op_sel_hi:[1,0,1]
	v_pk_fma_f32 v[38:39], v[216:217], v[166:167], v[128:129] op_sel_hi:[1,0,1]
	v_pk_fma_f32 v[32:33], v[218:219], v[166:167], v[130:131] op_sel_hi:[1,0,1]
	v_pk_fma_f32 v[34:35], v[220:221], v[166:167], v[132:133] op_sel_hi:[1,0,1]
	v_add_f32_e32 v136, v168, v134
	v_add_f32_e32 v136, v135, v136
	ds_write_b32 v95, v136 offset:1408
	ds_read_b128 v[190:193], v120 offset:16640
	ds_read_b128 v[194:197], v120 offset:16656
	ds_read_b128 v[198:201], v120 offset:16896
	ds_read_b128 v[202:205], v120 offset:16912
	ds_read_b128 v[206:209], v120 offset:17152
	ds_read_b128 v[210:213], v120 offset:17168
	ds_read_b128 v[214:217], v120 offset:17408
	ds_read_b128 v[218:221], v120 offset:17424
	ds_read_b128 v[222:225], v120 offset:17664
	ds_read_b128 v[226:229], v120 offset:17680
	ds_read_b32 v230, v96 offset:23808
	ds_read_b64 v[232:233], v121 offset:24784
	s_waitcnt lgkmcnt(12)
; #define SC_LOAD(t) { _Pragma("unroll") for (int q = 0; q < 5; ++q) { n[2 * q] = *(const LAS f32x4*)(opb + (t) * 320 + q * 64); n[2 * q + 1] = *(const LAS f32x4*)(opb + (t) * 320 + q * 64 + 4); } \
;                      nv = vvb[(t) * 64]; nbk = *(const LAS f32x2*)(scb + (t) * 4); }
; DI void scan_item(const __attribute__((address_space(4))) Args& a, LAS unsigned char* lds, int ws_, bool is_prompt, int seq, int h, int half, bool dry = false) {
;     ...
;         SC_LOAD(0)
; #pragma unroll 4
;         for (int t = 0; t < SC_CH; ++t) {
;             f32x4 c[10];
; #pragma unroll
;             for (int q = 0; q < 10; ++q) c[q] = n[q];
;             const float v0 = nv; const f32x2 bk = nbk;
;             SC_LOAD(t + 1)
;             __builtin_amdgcn_sched_barrier(0);
;             f32x2 aA = sp[0] * c[0].xy, aY = sp[0] * c[2].xy;
;             aA = sp[1] * c[0].zw + aA; aY = sp[1] * c[2].zw + aY;
;             aA = sp[2] * c[1].xy + aA; aY = sp[2] * c[3].xy + aY;
;             aA = sp[3] * c[1].zw + aA; aY = sp[3] * c[3].zw + aY;
;             float da = aA.x + aA.y, dy = aY.x + aY.y;
;             asm("s_nop 1\n\t"
;                 "v_add_f32_dpp %0, %0, %0 quad_perm:[1,0,3,2] row_mask:0xf bank_mask:0xf bound_ctrl:1\n\t"
;                 "v_add_f32_dpp %1, %1, %1 quad_perm:[1,0,3,2] row_mask:0xf bank_mask:0xf bound_ctrl:1\n\t"
;                 "s_nop 0\n\t"
;                 "v_add_f32_dpp %0, %0, %0 quad_perm:[2,3,0,1] row_mask:0xf bank_mask:0xf bound_ctrl:1\n\t"
;                 "v_add_f32_dpp %1, %1, %1 quad_perm:[2,3,0,1] row_mask:0xf bank_mask:0xf bound_ctrl:1\n\t"
;                 "s_nop 0\n\t"
;                 "v_add_f32_dpp %0, %0, %0 row_half_mirror row_mask:0xf bank_mask:0xf bound_ctrl:1\n\t"
;                 "v_add_f32_dpp %1, %1, %1 row_half_mirror row_mask:0xf bank_mask:0xf bound_ctrl:1"
;                 : "+v"(da), "+v"(dy));
;             {
;                 f32x2 t0;
;                 t0 = c[8].xy * v0; t0 = c[6].xy * da + t0; sp[0] = sp[0] * c[4].xy + t0;
;                 t0 = c[8].zw * v0; t0 = c[6].zw * da + t0; sp[1] = sp[1] * c[4].zw + t0;
;                 t0 = c[9].xy * v0; t0 = c[7].xy * da + t0; sp[2] = sp[2] * c[5].xy + t0;
;                 t0 = c[9].zw * v0; t0 = c[7].zw * da + t0; sp[3] = sp[3] * c[5].zw + t0;
;             }
;             ybb[t * 32] = dy + da * bk.x + v0 * bk.y;
;         }
	v_pk_mul_f32 v[122:123], v[38:39], v[42:43]
	v_pk_mul_f32 v[124:125], v[38:39], v[50:51]
	v_pk_fma_f32 v[122:123], v[36:37], v[40:41], v[122:123]
	v_pk_fma_f32 v[124:125], v[36:37], v[48:49], v[124:125]
	v_pk_fma_f32 v[122:123], v[32:33], v[44:45], v[122:123]
	v_pk_fma_f32 v[124:125], v[32:33], v[52:53], v[124:125]
	v_pk_fma_f32 v[122:123], v[34:35], v[46:47], v[122:123]
	v_pk_fma_f32 v[124:125], v[34:35], v[54:55], v[124:125]
	v_pk_mul_f32 v[126:127], v[72:73], v[94:95] op_sel_hi:[1,0]
	v_add_f32_e32 v166, v122, v123
	v_add_f32_e32 v168, v124, v125
	v_pk_mul_f32 v[128:129], v[74:75], v[94:95] op_sel_hi:[1,0]
	v_pk_mul_f32 v[130:131], v[76:77], v[94:95] op_sel_hi:[1,0]
	v_add_f32_dpp v166, v166, v166 quad_perm:[1,0,3,2] row_mask:0xf bank_mask:0xf bound_ctrl:1
	v_add_f32_dpp v168, v168, v168 quad_perm:[1,0,3,2] row_mask:0xf bank_mask:0xf bound_ctrl:1
	v_pk_mul_f32 v[132:133], v[78:79], v[94:95] op_sel_hi:[1,0]
	v_pk_fma_f32 v[126:127], v[36:37], v[56:57], v[126:127]
	v_add_f32_dpp v166, v166, v166 quad_perm:[2,3,0,1] row_mask:0xf bank_mask:0xf bound_ctrl:1
	v_add_f32_dpp v168, v168, v168 quad_perm:[2,3,0,1] row_mask:0xf bank_mask:0xf bound_ctrl:1
	v_pk_fma_f32 v[128:129], v[38:39], v[58:59], v[128:129]
	v_pk_fma_f32 v[130:131], v[32:33], v[60:61], v[130:131]
	v_add_f32_dpp v166, v166, v166 row_half_mirror row_mask:0xf bank_mask:0xf bound_ctrl:1
	v_add_f32_dpp v168, v168, v168 row_half_mirror row_mask:0xf bank_mask:0xf bound_ctrl:1
	v_pk_fma_f32 v[132:133], v[34:35], v[62:63], v[132:133]
	v_mov_b32_e32 v167, v94
	v_pk_mul_f32 v[134:135], v[166:167], v[108:109]
	v_pk_fma_f32 v[36:37], v[64:65], v[166:167], v[126:127] op_sel_hi:[1,0,1]
	v_pk_fma_f32 v[38:39], v[66:67], v[166:167], v[128:129] op_sel_hi:[1,0,1]
	v_pk_fma_f32 v[32:33], v[68:69], v[166:167], v[130:131] op_sel_hi:[1,0,1]
	v_pk_fma_f32 v[34:35], v[70:71], v[166:167], v[132:133] op_sel_hi:[1,0,1]
	v_add_f32_e32 v136, v168, v134
	v_add_f32_e32 v136, v135, v136
	ds_write_b32 v95, v136 offset:1536
	ds_read_b128 v[40:43], v120 offset:17920
	ds_read_b128 v[44:47], v120 offset:17936
	ds_read_b128 v[48:51], v120 offset:18176
	ds_read_b128 v[52:55], v120 offset:18192
	ds_read_b128 v[56:59], v120 offset:18432
	ds_read_b128 v[60:63], v120 offset:18448
	ds_read_b128 v[64:67], v120 offset:18688
	ds_read_b128 v[68:71], v120 offset:18704
	ds_read_b128 v[72:75], v120 offset:18944
	ds_read_b128 v[76:79], v120 offset:18960
	ds_read_b32 v94, v96 offset:24064
	ds_read_b64 v[108:109], v121 offset:24800
	s_waitcnt lgkmcnt(12)
	v_pk_mul_f32 v[122:123], v[38:39], v[192:193]
	v_pk_mul_f32 v[124:125], v[38:39], v[200:201]
	v_pk_fma_f32 v[122:123], v[36:37], v[190:191], v[122:123]
	v_pk_fma_f32 v[124:125], v[36:37], v[198:199], v[124:125]
	v_pk_fma_f32 v[122:123], v[32:33], v[194:195], v[122:123]
	v_pk_fma_f32 v[124:125], v[32:33], v[202:203], v[124:125]
	v_pk_fma_f32 v[122:123], v[34:35], v[196:197], v[122:123]
	v_pk_fma_f32 v[124:125], v[34:35], v[204:205], v[124:125]
	v_pk_mul_f32 v[126:127], v[222:223], v[230:231] op_sel_hi:[1,0]
	v_add_f32_e32 v166, v122, v123
	v_add_f32_e32 v168, v124, v125
	v_pk_mul_f32 v[128:129], v[224:225], v[230:231] op_sel_hi:[1,0]
	v_pk_mul_f32 v[130:131], v[226:227], v[230:231] op_sel_hi:[1,0]
	v_add_f32_dpp v166, v166, v166 quad_perm:[1,0,3,2] row_mask:0xf bank_mask:0xf bound_ctrl:1
	v_add_f32_dpp v168, v168, v168 quad_perm:[1,0,3,2] row_mask:0xf bank_mask:0xf bound_ctrl:1
	v_pk_mul_f32 v[132:133], v[228:229], v[230:231] op_sel_hi:[1,0]
	v_pk_fma_f32 v[126:127], v[36:37], v[206:207], v[126:127]
	v_add_f32_dpp v166, v166, v166 quad_perm:[2,3,0,1] row_mask:0xf bank_mask:0xf bound_ctrl:1
	v_add_f32_dpp v168, v168, v168 quad_perm:[2,3,0,1] row_mask:0xf bank_mask:0xf bound_ctrl:1
	v_pk_fma_f32 v[128:129], v[38:39], v[208:209], v[128:129]
	v_pk_fma_f32 v[130:131], v[32:33], v[210:211], v[130:131]
	v_add_f32_dpp v166, v166, v166 row_half_mirror row_mask:0xf bank_mask:0xf bound_ctrl:1
	v_add_f32_dpp v168, v168, v168 row_half_mirror row_mask:0xf bank_mask:0xf bound_ctrl:1
	v_pk_fma_f32 v[132:133], v[34:35], v[212:213], v[132:133]
	v_mov_b32_e32 v167, v230
	v_pk_mul_f32 v[134:135], v[166:167], v[232:233]
	v_pk_fma_f32 v[36:37], v[214:215], v[166:167], v[126:127] op_sel_hi:[1,0,1]
	v_pk_fma_f32 v[38:39], v[216:217], v[166:167], v[128:129] op_sel_hi:[1,0,1]
	v_pk_fma_f32 v[32:33], v[218:219], v[166:167], v[130:131] op_sel_hi:[1,0,1]
	v_pk_fma_f32 v[34:35], v[220:221], v[166:167], v[132:133] op_sel_hi:[1,0,1]
	v_add_f32_e32 v136, v168, v134
	v_add_f32_e32 v136, v135, v136
	ds_write_b32 v95, v136 offset:1664
	ds_read_b128 v[190:193], v120 offset:19200
	ds_read_b128 v[194:197], v120 offset:19216
	ds_read_b128 v[198:201], v120 offset:19456
	ds_read_b128 v[202:205], v120 offset:19472
	ds_read_b128 v[206:209], v120 offset:19712
	ds_read_b128 v[210:213], v120 offset:19728
	ds_read_b128 v[214:217], v120 offset:19968
	ds_read_b128 v[218:221], v120 offset:19984
	ds_read_b128 v[222:225], v120 offset:20224
	ds_read_b128 v[226:229], v120 offset:20240
	ds_read_b32 v230, v96 offset:24320
	ds_read_b64 v[232:233], v121 offset:24816
	s_waitcnt lgkmcnt(12)
; #define SC_LOAD(t) { _Pragma("unroll") for (int q = 0; q < 5; ++q) { n[2 * q] = *(const LAS f32x4*)(opb + (t) * 320 + q * 64); n[2 * q + 1] = *(const LAS f32x4*)(opb + (t) * 320 + q * 64 + 4); } \
;                      nv = vvb[(t) * 64]; nbk = *(const LAS f32x2*)(scb + (t) * 4); }
; DI void scan_item(const __attribute__((address_space(4))) Args& a, LAS unsigned char* lds, int ws_, bool is_prompt, int seq, int h, int half, bool dry = false) {
;     ...
;         SC_LOAD(0)
; #pragma unroll 4
;         for (int t = 0; t < SC_CH; ++t) {
;             f32x4 c[10];
; #pragma unroll
;             for (int q = 0; q < 10; ++q) c[q] = n[q];
;             const float v0 = nv; const f32x2 bk = nbk;
;             SC_LOAD(t + 1)
;             __builtin_amdgcn_sched_barrier(0);
;             f32x2 aA = sp[0] * c[0].xy, aY = sp[0] * c[2].xy;
;             aA = sp[1] * c[0].zw + aA; aY = sp[1] * c[2].zw + aY;
;             aA = sp[2] * c[1].xy + aA; aY = sp[2] * c[3].xy + aY;
;             aA = sp[3] * c[1].zw + aA; aY = sp[3] * c[3].zw + aY;
;             float da = aA.x + aA.y, dy = aY.x + aY.y;
;             asm("s_nop 1\n\t"
;                 "v_add_f32_dpp %0, %0, %0 quad_perm:[1,0,3,2] row_mask:0xf bank_mask:0xf bound_ctrl:1\n\t"
;                 "v_add_f32_dpp %1, %1, %1 quad_perm:[1,0,3,2] row_mask:0xf bank_mask:0xf bound_ctrl:1\n\t"
;                 "s_nop 0\n\t"
;                 "v_add_f32_dpp %0, %0, %0 quad_perm:[2,3,0,1] row_mask:0xf bank_mask:0xf bound_ctrl:1\n\t"
;                 "v_add_f32_dpp %1, %1, %1 quad_perm:[2,3,0,1] row_mask:0xf bank_mask:0xf bound_ctrl:1\n\t"
;                 "s_nop 0\n\t"
;                 "v_add_f32_dpp %0, %0, %0 row_half_mirror row_mask:0xf bank_mask:0xf bound_ctrl:1\n\t"
;                 "v_add_f32_dpp %1, %1, %1 row_half_mirror row_mask:0xf bank_mask:0xf bound_ctrl:1"
;                 : "+v"(da), "+v"(dy));
;             {
;                 f32x2 t0;
;                 t0 = c[8].xy * v0; t0 = c[6].xy * da + t0; sp[0] = sp[0] * c[4].xy + t0;
;                 t0 = c[8].zw * v0; t0 = c[6].zw * da + t0; sp[1] = sp[1] * c[4].zw + t0;
;                 t0 = c[9].xy * v0; t0 = c[7].xy * da + t0; sp[2] = sp[2] * c[5].xy + t0;
;                 t0 = c[9].zw * v0; t0 = c[7].zw * da + t0; sp[3] = sp[3] * c[5].zw + t0;
;             }
;             ybb[t * 32] = dy + da * bk.x + v0 * bk.y;
;         }
	v_pk_mul_f32 v[122:123], v[38:39], v[42:43]
	v_pk_mul_f32 v[124:125], v[38:39], v[50:51]
	v_pk_fma_f32 v[122:123], v[36:37], v[40:41], v[122:123]
	v_pk_fma_f32 v[124:125], v[36:37], v[48:49], v[124:125]
	v_pk_fma_f32 v[122:123], v[32:33], v[44:45], v[122:123]
	v_pk_fma_f32 v[124:125], v[32:33], v[52:53], v[124:125]
	v_pk_fma_f32 v[122:123], v[34:35], v[46:47], v[122:123]
	v_pk_fma_f32 v[124:125], v[34:35], v[54:55], v[124:125]
	v_pk_mul_f32 v[126:127], v[72:73], v[94:95] op_sel_hi:[1,0]
	v_add_f32_e32 v166, v122, v123
	v_add_f32_e32 v168, v124, v125
	v_pk_mul_f32 v[128:129], v[74:75], v[94:95] op_sel_hi:[1,0]
	v_pk_mul_f32 v[130:131], v[76:77], v[94:95] op_sel_hi:[1,0]
	v_add_f32_dpp v166, v166, v166 quad_perm:[1,0,3,2] row_mask:0xf bank_mask:0xf bound_ctrl:1
	v_add_f32_dpp v168, v168, v168 quad_perm:[1,0,3,2] row_mask:0xf bank_mask:0xf bound_ctrl:1
	v_pk_mul_f32 v[132:133], v[78:79], v[94:95] op_sel_hi:[1,0]
	v_pk_fma_f32 v[126:127], v[36:37], v[56:57], v[126:127]
	v_add_f32_dpp v166, v166, v166 quad_perm:[2,3,0,1] row_mask:0xf bank_mask:0xf bound_ctrl:1
	v_add_f32_dpp v168, v168, v168 quad_perm:[2,3,0,1] row_mask:0xf bank_mask:0xf bound_ctrl:1
	v_pk_fma_f32 v[128:129], v[38:39], v[58:59], v[128:129]
	v_pk_fma_f32 v[130:131], v[32:33], v[60:61], v[130:131]
	v_add_f32_dpp v166, v166, v166 row_half_mirror row_mask:0xf bank_mask:0xf bound_ctrl:1
	v_add_f32_dpp v168, v168, v168 row_half_mirror row_mask:0xf bank_mask:0xf bound_ctrl:1
	v_pk_fma_f32 v[132:133], v[34:35], v[62:63], v[132:133]
	v_mov_b32_e32 v167, v94
	v_pk_mul_f32 v[134:135], v[166:167], v[108:109]
	v_pk_fma_f32 v[36:37], v[64:65], v[166:167], v[126:127] op_sel_hi:[1,0,1]
	v_pk_fma_f32 v[38:39], v[66:67], v[166:167], v[128:129] op_sel_hi:[1,0,1]
	v_pk_fma_f32 v[32:33], v[68:69], v[166:167], v[130:131] op_sel_hi:[1,0,1]
	v_pk_fma_f32 v[34:35], v[70:71], v[166:167], v[132:133] op_sel_hi:[1,0,1]
	v_add_f32_e32 v136, v168, v134
	v_add_f32_e32 v136, v135, v136
	ds_write_b32 v95, v136 offset:1792
	s_waitcnt lgkmcnt(0)
	v_pk_mul_f32 v[122:123], v[38:39], v[192:193]
	v_pk_mul_f32 v[124:125], v[38:39], v[200:201]
	v_pk_fma_f32 v[122:123], v[36:37], v[190:191], v[122:123]
	v_pk_fma_f32 v[124:125], v[36:37], v[198:199], v[124:125]
	v_pk_fma_f32 v[122:123], v[32:33], v[194:195], v[122:123]
	v_pk_fma_f32 v[124:125], v[32:33], v[202:203], v[124:125]
	v_pk_fma_f32 v[122:123], v[34:35], v[196:197], v[122:123]
	v_pk_fma_f32 v[124:125], v[34:35], v[204:205], v[124:125]
	v_pk_mul_f32 v[126:127], v[222:223], v[230:231] op_sel_hi:[1,0]
	v_add_f32_e32 v166, v122, v123
	v_add_f32_e32 v168, v124, v125
	v_pk_mul_f32 v[128:129], v[224:225], v[230:231] op_sel_hi:[1,0]
	v_pk_mul_f32 v[130:131], v[226:227], v[230:231] op_sel_hi:[1,0]
	v_add_f32_dpp v166, v166, v166 quad_perm:[1,0,3,2] row_mask:0xf bank_mask:0xf bound_ctrl:1
	v_add_f32_dpp v168, v168, v168 quad_perm:[1,0,3,2] row_mask:0xf bank_mask:0xf bound_ctrl:1
	v_pk_mul_f32 v[132:133], v[228:229], v[230:231] op_sel_hi:[1,0]
	v_pk_fma_f32 v[126:127], v[36:37], v[206:207], v[126:127]
	v_add_f32_dpp v166, v166, v166 quad_perm:[2,3,0,1] row_mask:0xf bank_mask:0xf bound_ctrl:1
	v_add_f32_dpp v168, v168, v168 quad_perm:[2,3,0,1] row_mask:0xf bank_mask:0xf bound_ctrl:1
	v_pk_fma_f32 v[128:129], v[38:39], v[208:209], v[128:129]
	v_pk_fma_f32 v[130:131], v[32:33], v[210:211], v[130:131]
	v_add_f32_dpp v166, v166, v166 row_half_mirror row_mask:0xf bank_mask:0xf bound_ctrl:1
	v_add_f32_dpp v168, v168, v168 row_half_mirror row_mask:0xf bank_mask:0xf bound_ctrl:1
	v_pk_fma_f32 v[132:133], v[34:35], v[212:213], v[132:133]
	v_mov_b32_e32 v167, v230
	v_pk_mul_f32 v[134:135], v[166:167], v[232:233]
	v_pk_fma_f32 v[36:37], v[214:215], v[166:167], v[126:127] op_sel_hi:[1,0,1]
	v_pk_fma_f32 v[38:39], v[216:217], v[166:167], v[128:129] op_sel_hi:[1,0,1]
	v_pk_fma_f32 v[32:33], v[218:219], v[166:167], v[130:131] op_sel_hi:[1,0,1]
	v_pk_fma_f32 v[34:35], v[220:221], v[166:167], v[132:133] op_sel_hi:[1,0,1]
	v_add_f32_e32 v136, v168, v134
	v_add_f32_e32 v136, v135, v136
	ds_write_b32 v95, v136 offset:1920
	s_add_i32 s24, s24, 1
	s_branch .LBB0_1524
